# in GEMM: half-1 tile bases formed once per iteration at the loop edge and reused for both k-steps through the instruction offset (8 fewer scalar ops between MFMAs per iteration)
# baseline (speedup 1.0000x reference)
; #define PG8_STAGE(bufoff, gbase, voff) do { _Pragma("unroll") for (int _i = 0; _i < 2; ++_i) \
;         __builtin_amdgcn_global_load_lds((const unsigned*)((const char*)(gbase) + (voff)[_i]), (LAS unsigned*)(lds + (bufoff) + ldsw + _i * 8192), 16, 0, 0); } while (0)
; #define PG8_LDA(dst, b, h) do { _Pragma("unroll") for (int m = 0; m < 4; ++m) _Pragma("unroll") for (int k = 0; k < 2; ++k) dst[m][k] = *(const LAS bf16x8*)(lds + PG8_SA(b, h) + aoff + m * 2048 + k * 1024); } while (0)
; #define PG8_LDB(dst, b, h) do { _Pragma("unroll") for (int n = 0; n < 2; ++n) _Pragma("unroll") for (int k = 0; k < 2; ++k) dst[n][k] = *(const LAS bf16x8*)(lds + PG8_SB(b, h) + boff + n * 2048 + k * 1024); } while (0)
; #define PG8_MMA(ai, bj, At, Bt) do { __builtin_amdgcn_s_setprio(1); _Pragma("unroll") for (int m = 0; m < 4; ++m) _Pragma("unroll") for (int n = 0; n < 2; ++n) _Pragma("unroll") for (int k = 0; k < 2; ++k) \
;         acc[ai][bj][m][n] = __builtin_amdgcn_mfma_f32_16x16x32_bf16(Bt[n][k], At[m][k], acc[ai][bj][m][n], 0, 0, 0); __builtin_amdgcn_s_setprio(0); } while (0)
; #define PG8_WAIT_V(n) asm volatile("s_waitcnt vmcnt(" #n ")" ::: "memory")
; #define PG8_WAIT_L(n) asm volatile("s_waitcnt lgkmcnt(" #n ")" ::: "memory")
; template <class Epi, int LDA, int LDB, int KK>
; __device__ __forceinline__ void gemm_phase(int wv, LAS unsigned char* lds, const Gemm g, const StaticOrder& S, const Epi& E) {
;     ...
;           for (; t < tend; t += 2) {
;             const bool last = (t == nt - 2);
;             const char* a1 = cA + (size_t)(t + 1) * kstep;
;             const char* a2 = last ? nA : cA + (size_t)(t + 2) * kstep; const char* b2 = last ? nB : cB + (size_t)(t + 2) * kstep;
;             const char* a3 = a2 + kstep; const char* b3 = b2 + kstep;
;             PG8_LDB(B0, 0, 0); PG8_SCHED; PG8_LDA(At, 0, 0); PG8_STAGE(PG8_SA(1, 1), a1 + hstepA, voffA);
;             PG8_WAIT_L(8); PG8_BAR; PG8_WAIT_L(0); PG8_MMA(0, 0, At, B0); PG8_BAR; PG8_SCHED;
;             PG8_LDB(B1, 0, 1); PG8_STAGE(PG8_SB(0, 0), b2, voffB);
;             PG8_BAR; PG8_WAIT_L(0); PG8_MMA(0, 1, At, B1); PG8_BAR;
;             PG8_LDA(At, 0, 1); PG8_STAGE(PG8_SA(0, 0), a2, voffA);
;             PG8_BAR; PG8_WAIT_L(0); PG8_MMA(1, 0, At, B0); PG8_BAR; PG8_SCHED;
;             PG8_STAGE(PG8_SB(0, 1), b2 + hstepB, voffB);
;             PG8_WAIT_V(6); PG8_BAR; PG8_MMA(1, 1, At, B1); PG8_BAR;
.Lin_loop:
	s_add_u32 s34, s6, 0xfff80080
	s_addc_u32 s35, s7, -1
	s_cmp_eq_u32 s77, 28
	s_cselect_b32 s37, s23, s35
	s_cselect_b32 s36, s73, s34
	s_cselect_b32 s35, s21, s76
	s_cselect_b32 s34, s74, s75
	s_add_u32 s98, s34, 0x80000
	s_addc_u32 s99, s35, 0
	s_add_u32 s100, s36, 0x80000
	s_addc_u32 s101, s37, 0
	s_waitcnt lgkmcnt(0)
	v_mfma_f32_16x16x32_bf16 v[128:131], v[144:147], v[164:167], v[128:131]
	ds_read_b128 v[202:205], v197 offset:1024
	v_mfma_f32_16x16x32_bf16 v[124:127], v[152:155], v[164:167], v[124:127]
	ds_read_b128 v[206:209], v197 offset:3072
	v_mfma_f32_16x16x32_bf16 v[120:123], v[156:159], v[164:167], v[120:123]
	ds_read_b128 v[210:213], v197 offset:17408
	v_mfma_f32_16x16x32_bf16 v[116:119], v[160:163], v[164:167], v[116:119]
	ds_read_b128 v[214:217], v197 offset:19456
	v_mfma_f32_16x16x32_bf16 v[112:115], v[144:147], v[168:171], v[112:115]
	ds_read_b128 v[180:183], v151 offset:1024
	v_mfma_f32_16x16x32_bf16 v[108:111], v[152:155], v[168:171], v[108:111]
	ds_read_b128 v[184:187], v151 offset:3072
	v_mfma_f32_16x16x32_bf16 v[104:107], v[156:159], v[168:171], v[104:107]
	ds_read_b128 v[188:191], v151 offset:5120
	v_mfma_f32_16x16x32_bf16 v[96:99], v[160:163], v[168:171], v[96:99]
	ds_read_b128 v[192:195], v151 offset:7168
	v_mfma_f32_16x16x32_bf16 v[100:103], v[144:147], v[172:175], v[100:103]
	v_mfma_f32_16x16x32_bf16 v[92:95], v[152:155], v[172:175], v[92:95]
	v_mfma_f32_16x16x32_bf16 v[88:91], v[156:159], v[172:175], v[88:91]
	v_mfma_f32_16x16x32_bf16 v[84:87], v[160:163], v[172:175], v[84:87]
	v_mfma_f32_16x16x32_bf16 v[80:83], v[144:147], v[176:179], v[80:83]
	v_mfma_f32_16x16x32_bf16 v[76:79], v[152:155], v[176:179], v[76:79]
	v_mfma_f32_16x16x32_bf16 v[72:75], v[156:159], v[176:179], v[72:75]
	v_mfma_f32_16x16x32_bf16 v[68:71], v[160:163], v[176:179], v[68:71]
	s_waitcnt vmcnt(8) lgkmcnt(0)
	s_barrier
	v_mfma_f32_16x16x32_bf16 v[128:131], v[202:205], v[180:183], v[128:131]
	ds_read_b128 v[164:167], v151 offset:16384
	v_mfma_f32_16x16x32_bf16 v[124:127], v[206:209], v[180:183], v[124:127]
	ds_read_b128 v[168:171], v151 offset:18432
	v_mfma_f32_16x16x32_bf16 v[120:123], v[210:213], v[180:183], v[120:123]
	ds_read_b128 v[172:175], v151 offset:20480
	v_mfma_f32_16x16x32_bf16 v[116:119], v[214:217], v[180:183], v[116:119]
	ds_read_b128 v[176:179], v151 offset:22528
	v_mfma_f32_16x16x32_bf16 v[112:115], v[202:205], v[184:187], v[112:115]
	s_add_i32 m0, s31, 0x10000
	v_mfma_f32_16x16x32_bf16 v[108:111], v[206:209], v[184:187], v[108:111]
	global_load_lds_dwordx4 v132, s[34:35]
	v_mfma_f32_16x16x32_bf16 v[104:107], v[210:213], v[184:187], v[104:107]
	v_mfma_f32_16x16x32_bf16 v[96:99], v[214:217], v[184:187], v[96:99]
	s_add_i32 m0, s31, 0x12000
	v_mfma_f32_16x16x32_bf16 v[100:103], v[202:205], v[188:191], v[100:103]
	global_load_lds_dwordx4 v136, s[34:35]
	v_mfma_f32_16x16x32_bf16 v[92:95], v[206:209], v[188:191], v[92:95]
	v_mfma_f32_16x16x32_bf16 v[88:91], v[210:213], v[188:191], v[88:91]
	s_mov_b32 m0, s31
	v_mfma_f32_16x16x32_bf16 v[84:87], v[214:217], v[188:191], v[84:87]
	global_load_lds_dwordx4 v0, s[36:37]
	v_mfma_f32_16x16x32_bf16 v[80:83], v[202:205], v[192:195], v[80:83]
	v_mfma_f32_16x16x32_bf16 v[76:79], v[206:209], v[192:195], v[76:79]
	v_mfma_f32_16x16x32_bf16 v[72:75], v[210:213], v[192:195], v[72:75]
	v_mfma_f32_16x16x32_bf16 v[68:71], v[214:217], v[192:195], v[68:71]
	s_waitcnt lgkmcnt(0)
	v_mfma_f32_16x16x32_bf16 v[64:67], v[144:147], v[164:167], v[64:67]
	ds_read_b128 v[180:183], v151 offset:17408
	v_mfma_f32_16x16x32_bf16 v[60:63], v[152:155], v[164:167], v[60:63]
	ds_read_b128 v[184:187], v151 offset:19456
	v_mfma_f32_16x16x32_bf16 v[56:59], v[156:159], v[164:167], v[56:59]
	ds_read_b128 v[188:191], v151 offset:21504
	v_mfma_f32_16x16x32_bf16 v[52:55], v[160:163], v[164:167], v[52:55]
	ds_read_b128 v[192:195], v151 offset:23552
	v_mfma_f32_16x16x32_bf16 v[48:51], v[144:147], v[168:171], v[48:51]
	s_add_i32 m0, s31, 0x2000
	v_mfma_f32_16x16x32_bf16 v[44:47], v[152:155], v[168:171], v[44:47]
	global_load_lds_dwordx4 v134, s[36:37]
	v_mfma_f32_16x16x32_bf16 v[40:43], v[156:159], v[168:171], v[40:43]
	v_mfma_f32_16x16x32_bf16 v[32:35], v[160:163], v[168:171], v[32:35]
	s_add_i32 m0, s31, 0x14000
	v_mfma_f32_16x16x32_bf16 v[36:39], v[144:147], v[172:175], v[36:39]
	global_load_lds_dwordx4 v132, s[98:99]
	v_mfma_f32_16x16x32_bf16 v[28:31], v[152:155], v[172:175], v[28:31]
	v_mfma_f32_16x16x32_bf16 v[24:27], v[156:159], v[172:175], v[24:27]
	s_add_i32 m0, s31, 0x16000
	v_mfma_f32_16x16x32_bf16 v[20:23], v[160:163], v[172:175], v[20:23]
	global_load_lds_dwordx4 v136, s[98:99]
	v_mfma_f32_16x16x32_bf16 v[16:19], v[144:147], v[176:179], v[16:19]
	v_mfma_f32_16x16x32_bf16 v[12:15], v[152:155], v[176:179], v[12:15]
	v_mfma_f32_16x16x32_bf16 v[8:11], v[156:159], v[176:179], v[8:11]
	v_mfma_f32_16x16x32_bf16 v[4:7], v[160:163], v[176:179], v[4:7]
	s_waitcnt vmcnt(8) lgkmcnt(0)
	s_barrier
; #define PG8_STAGE(bufoff, gbase, voff) do { _Pragma("unroll") for (int _i = 0; _i < 2; ++_i) \
;         __builtin_amdgcn_global_load_lds((const unsigned*)((const char*)(gbase) + (voff)[_i]), (LAS unsigned*)(lds + (bufoff) + ldsw + _i * 8192), 16, 0, 0); } while (0)
; #define PG8_LDA(dst, b, h) do { _Pragma("unroll") for (int m = 0; m < 4; ++m) _Pragma("unroll") for (int k = 0; k < 2; ++k) dst[m][k] = *(const LAS bf16x8*)(lds + PG8_SA(b, h) + aoff + m * 2048 + k * 1024); } while (0)
; #define PG8_LDB(dst, b, h) do { _Pragma("unroll") for (int n = 0; n < 2; ++n) _Pragma("unroll") for (int k = 0; k < 2; ++k) dst[n][k] = *(const LAS bf16x8*)(lds + PG8_SB(b, h) + boff + n * 2048 + k * 1024); } while (0)
; #define PG8_MMA(ai, bj, At, Bt) do { __builtin_amdgcn_s_setprio(1); _Pragma("unroll") for (int m = 0; m < 4; ++m) _Pragma("unroll") for (int n = 0; n < 2; ++n) _Pragma("unroll") for (int k = 0; k < 2; ++k) \
;         acc[ai][bj][m][n] = __builtin_amdgcn_mfma_f32_16x16x32_bf16(Bt[n][k], At[m][k], acc[ai][bj][m][n], 0, 0, 0); __builtin_amdgcn_s_setprio(0); } while (0)
; #define PG8_WAIT_V(n) asm volatile("s_waitcnt vmcnt(" #n ")" ::: "memory")
; #define PG8_WAIT_L(n) asm volatile("s_waitcnt lgkmcnt(" #n ")" ::: "memory")
; #define PG8_BAR __builtin_amdgcn_s_barrier()
; #define PG8_SCHED __builtin_amdgcn_sched_barrier(0)
; template <class Epi, int LDA, int LDB, int KK>
; __device__ __forceinline__ void gemm_phase(int wv, LAS unsigned char* lds, const Gemm g, const StaticOrder& S, const Epi& E) {
;     ...
;             PG8_LDB(B0, 1, 0); PG8_SCHED; PG8_LDA(At, 1, 0); PG8_STAGE(PG8_SA(0, 1), a2 + hstepA, voffA);
;             PG8_WAIT_L(8); PG8_BAR; PG8_WAIT_L(0); PG8_MMA(0, 0, At, B0); PG8_BAR; PG8_SCHED;
;             PG8_LDB(B1, 1, 1); PG8_STAGE(PG8_SB(1, 0), b3, voffB);
;             PG8_BAR; PG8_WAIT_L(0); PG8_MMA(0, 1, At, B1); PG8_BAR;
;             PG8_LDA(At, 1, 1); PG8_STAGE(PG8_SA(1, 0), a3, voffA);
;             PG8_BAR; PG8_WAIT_L(0); PG8_MMA(1, 0, At, B0); PG8_BAR; PG8_SCHED;
;             PG8_STAGE(PG8_SB(1, 1), b3 + hstepB, voffB);
;             PG8_WAIT_V(6); PG8_BAR; PG8_MMA(1, 1, At, B1); PG8_BAR;
	v_mfma_f32_16x16x32_bf16 v[64:67], v[202:205], v[180:183], v[64:67]
	ds_read_b128 v[144:147], v197 offset:32768
	v_mfma_f32_16x16x32_bf16 v[60:63], v[206:209], v[180:183], v[60:63]
	ds_read_b128 v[152:155], v197 offset:34816
	v_mfma_f32_16x16x32_bf16 v[56:59], v[210:213], v[180:183], v[56:59]
	ds_read_b128 v[156:159], v197 offset:49152
	v_mfma_f32_16x16x32_bf16 v[52:55], v[214:217], v[180:183], v[52:55]
	ds_read_b128 v[160:163], v197 offset:51200
	v_mfma_f32_16x16x32_bf16 v[48:51], v[202:205], v[184:187], v[48:51]
	ds_read_b128 v[164:167], v151 offset:32768
	v_mfma_f32_16x16x32_bf16 v[44:47], v[206:209], v[184:187], v[44:47]
	ds_read_b128 v[168:171], v151 offset:34816
	v_mfma_f32_16x16x32_bf16 v[40:43], v[210:213], v[184:187], v[40:43]
	ds_read_b128 v[172:175], v151 offset:36864
	v_mfma_f32_16x16x32_bf16 v[32:35], v[214:217], v[184:187], v[32:35]
	ds_read_b128 v[176:179], v151 offset:38912
	v_mfma_f32_16x16x32_bf16 v[36:39], v[202:205], v[188:191], v[36:39]
	s_add_i32 m0, s31, 0x4000
	v_mfma_f32_16x16x32_bf16 v[28:31], v[206:209], v[188:191], v[28:31]
	global_load_lds_dwordx4 v0, s[100:101]
	v_mfma_f32_16x16x32_bf16 v[24:27], v[210:213], v[188:191], v[24:27]
	v_mfma_f32_16x16x32_bf16 v[20:23], v[214:217], v[188:191], v[20:23]
	s_add_i32 m0, s31, 0x6000
	v_mfma_f32_16x16x32_bf16 v[16:19], v[202:205], v[192:195], v[16:19]
	global_load_lds_dwordx4 v134, s[100:101]
	v_mfma_f32_16x16x32_bf16 v[12:15], v[206:209], v[192:195], v[12:15]
	v_mfma_f32_16x16x32_bf16 v[8:11], v[210:213], v[192:195], v[8:11]
	v_mfma_f32_16x16x32_bf16 v[4:7], v[214:217], v[192:195], v[4:7]
	s_waitcnt lgkmcnt(0)
	v_mfma_f32_16x16x32_bf16 v[128:131], v[144:147], v[164:167], v[128:131]
	ds_read_b128 v[202:205], v197 offset:33792
	v_mfma_f32_16x16x32_bf16 v[124:127], v[152:155], v[164:167], v[124:127]
	ds_read_b128 v[206:209], v197 offset:35840
	v_mfma_f32_16x16x32_bf16 v[120:123], v[156:159], v[164:167], v[120:123]
	ds_read_b128 v[210:213], v197 offset:50176
	v_mfma_f32_16x16x32_bf16 v[116:119], v[160:163], v[164:167], v[116:119]
	ds_read_b128 v[214:217], v197 offset:52224
	v_mfma_f32_16x16x32_bf16 v[112:115], v[144:147], v[168:171], v[112:115]
	ds_read_b128 v[180:183], v151 offset:33792
	v_mfma_f32_16x16x32_bf16 v[108:111], v[152:155], v[168:171], v[108:111]
	ds_read_b128 v[184:187], v151 offset:35840
	v_mfma_f32_16x16x32_bf16 v[104:107], v[156:159], v[168:171], v[104:107]
	ds_read_b128 v[188:191], v151 offset:37888
	v_mfma_f32_16x16x32_bf16 v[96:99], v[160:163], v[168:171], v[96:99]
	ds_read_b128 v[192:195], v151 offset:39936
	v_mfma_f32_16x16x32_bf16 v[100:103], v[144:147], v[172:175], v[100:103]
	v_mfma_f32_16x16x32_bf16 v[92:95], v[152:155], v[172:175], v[92:95]
	v_mfma_f32_16x16x32_bf16 v[88:91], v[156:159], v[172:175], v[88:91]
	v_mfma_f32_16x16x32_bf16 v[84:87], v[160:163], v[172:175], v[84:87]
	v_mfma_f32_16x16x32_bf16 v[80:83], v[144:147], v[176:179], v[80:83]
	v_mfma_f32_16x16x32_bf16 v[76:79], v[152:155], v[176:179], v[76:79]
	v_mfma_f32_16x16x32_bf16 v[72:75], v[156:159], v[176:179], v[72:75]
	v_mfma_f32_16x16x32_bf16 v[68:71], v[160:163], v[176:179], v[68:71]
	s_waitcnt vmcnt(8) lgkmcnt(0)
	s_barrier
	v_mfma_f32_16x16x32_bf16 v[128:131], v[202:205], v[180:183], v[128:131]
	ds_read_b128 v[164:167], v151 offset:49152
	v_mfma_f32_16x16x32_bf16 v[124:127], v[206:209], v[180:183], v[124:127]
	ds_read_b128 v[168:171], v151 offset:51200
	v_mfma_f32_16x16x32_bf16 v[120:123], v[210:213], v[180:183], v[120:123]
	ds_read_b128 v[172:175], v151 offset:53248
	v_mfma_f32_16x16x32_bf16 v[116:119], v[214:217], v[180:183], v[116:119]
	ds_read_b128 v[176:179], v151 offset:55296
	v_mfma_f32_16x16x32_bf16 v[112:115], v[202:205], v[184:187], v[112:115]
	s_add_i32 m0, s31, 0x17f80
	v_mfma_f32_16x16x32_bf16 v[108:111], v[206:209], v[184:187], v[108:111]
	global_load_lds_dwordx4 v132, s[34:35] offset:128
	v_mfma_f32_16x16x32_bf16 v[104:107], v[210:213], v[184:187], v[104:107]
	v_mfma_f32_16x16x32_bf16 v[96:99], v[214:217], v[184:187], v[96:99]
	s_add_i32 m0, s31, 0x19f80
	v_mfma_f32_16x16x32_bf16 v[100:103], v[202:205], v[188:191], v[100:103]
	global_load_lds_dwordx4 v136, s[34:35] offset:128
	v_mfma_f32_16x16x32_bf16 v[92:95], v[206:209], v[188:191], v[92:95]
	v_mfma_f32_16x16x32_bf16 v[88:91], v[210:213], v[188:191], v[88:91]
	s_add_i32 m0, s31, 0x7f80
	v_mfma_f32_16x16x32_bf16 v[84:87], v[214:217], v[188:191], v[84:87]
	global_load_lds_dwordx4 v0, s[36:37] offset:128
	v_mfma_f32_16x16x32_bf16 v[80:83], v[202:205], v[192:195], v[80:83]
	v_mfma_f32_16x16x32_bf16 v[76:79], v[206:209], v[192:195], v[76:79]
	v_mfma_f32_16x16x32_bf16 v[72:75], v[210:213], v[192:195], v[72:75]
	v_mfma_f32_16x16x32_bf16 v[68:71], v[214:217], v[192:195], v[68:71]
	s_waitcnt lgkmcnt(0)
	v_mfma_f32_16x16x32_bf16 v[64:67], v[144:147], v[164:167], v[64:67]
	ds_read_b128 v[180:183], v151 offset:50176
	v_mfma_f32_16x16x32_bf16 v[60:63], v[152:155], v[164:167], v[60:63]
	ds_read_b128 v[184:187], v151 offset:52224
	v_mfma_f32_16x16x32_bf16 v[56:59], v[156:159], v[164:167], v[56:59]
	ds_read_b128 v[188:191], v151 offset:54272
	v_mfma_f32_16x16x32_bf16 v[52:55], v[160:163], v[164:167], v[52:55]
	ds_read_b128 v[192:195], v151 offset:56320
	v_mfma_f32_16x16x32_bf16 v[48:51], v[144:147], v[168:171], v[48:51]
	s_add_i32 m0, s31, 0x9f80
	v_mfma_f32_16x16x32_bf16 v[44:47], v[152:155], v[168:171], v[44:47]
	global_load_lds_dwordx4 v134, s[36:37] offset:128
	v_mfma_f32_16x16x32_bf16 v[40:43], v[156:159], v[168:171], v[40:43]
	v_mfma_f32_16x16x32_bf16 v[32:35], v[160:163], v[168:171], v[32:35]
	s_add_i32 m0, s31, 0x1bf80
	v_mfma_f32_16x16x32_bf16 v[36:39], v[144:147], v[172:175], v[36:39]
	global_load_lds_dwordx4 v132, s[98:99] offset:128
	v_mfma_f32_16x16x32_bf16 v[28:31], v[152:155], v[172:175], v[28:31]
	v_mfma_f32_16x16x32_bf16 v[24:27], v[156:159], v[172:175], v[24:27]
	s_add_i32 m0, s31, 0x1df80
	v_mfma_f32_16x16x32_bf16 v[20:23], v[160:163], v[172:175], v[20:23]
	global_load_lds_dwordx4 v136, s[98:99] offset:128
	v_mfma_f32_16x16x32_bf16 v[16:19], v[144:147], v[176:179], v[16:19]
	v_mfma_f32_16x16x32_bf16 v[12:15], v[152:155], v[176:179], v[12:15]
	v_mfma_f32_16x16x32_bf16 v[8:11], v[156:159], v[176:179], v[8:11]
	v_mfma_f32_16x16x32_bf16 v[4:7], v[160:163], v[176:179], v[4:7]
	s_waitcnt vmcnt(8) lgkmcnt(0)
	s_barrier
; #define LAS __attribute__((address_space(3)))
; #define PG8_STAGE(bufoff, gbase, voff) do { _Pragma("unroll") for (int _i = 0; _i < 2; ++_i) \
;         __builtin_amdgcn_global_load_lds((const unsigned*)((const char*)(gbase) + (voff)[_i]), (LAS unsigned*)(lds + (bufoff) + ldsw + _i * 8192), 16, 0, 0); } while (0)
; #define PG8_LDA(dst, b, h) do { _Pragma("unroll") for (int m = 0; m < 4; ++m) _Pragma("unroll") for (int k = 0; k < 2; ++k) dst[m][k] = *(const LAS bf16x8*)(lds + PG8_SA(b, h) + aoff + m * 2048 + k * 1024); } while (0)
; #define PG8_MMA(ai, bj, At, Bt) do { __builtin_amdgcn_s_setprio(1); _Pragma("unroll") for (int m = 0; m < 4; ++m) _Pragma("unroll") for (int n = 0; n < 2; ++n) _Pragma("unroll") for (int k = 0; k < 2; ++k) \
;         acc[ai][bj][m][n] = __builtin_amdgcn_mfma_f32_16x16x32_bf16(Bt[n][k], At[m][k], acc[ai][bj][m][n], 0, 0, 0); __builtin_amdgcn_s_setprio(0); } while (0)
; #define PG8_WAIT_V(n) asm volatile("s_waitcnt vmcnt(" #n ")" ::: "memory")
; #define PG8_WAIT_L(n) asm volatile("s_waitcnt lgkmcnt(" #n ")" ::: "memory")
; #define PG8_BAR __builtin_amdgcn_s_barrier()
; #define PG8_SCHED __builtin_amdgcn_sched_barrier(0)
; template <class Epi, int LDA, int LDB, int KK>
; __device__ __forceinline__ void gemm_phase(int wv, LAS unsigned char* lds, const Gemm g, const StaticOrder& S, const Epi& E) {
;     ...
;             PG8_LDA(At, 1, 1); PG8_STAGE(PG8_SA(1, 0), a3, voffA);
;             PG8_BAR; PG8_WAIT_L(0); PG8_MMA(1, 0, At, B0); PG8_BAR; PG8_SCHED;
;             PG8_STAGE(PG8_SB(1, 1), b3 + hstepB, voffB);
;             PG8_WAIT_V(6); PG8_BAR; PG8_MMA(1, 1, At, B1); PG8_BAR;
;           }
;           if constexpr (Epi::HAS_MID) { if (seg < Epi::NSEG - 1) E.mid(acc, cur, seg, wr, wc, fr, fq); }
;         }
;         E(acc, cur, wr, wc, fr, fq, (const LAS float*)(lds + 131072 + (ui % 3) * 1024));
	v_mfma_f32_16x16x32_bf16 v[64:67], v[202:205], v[180:183], v[64:67]
	ds_read_b128 v[144:147], v197 offset:0
	v_mfma_f32_16x16x32_bf16 v[60:63], v[206:209], v[180:183], v[60:63]
	ds_read_b128 v[152:155], v197 offset:2048
	v_mfma_f32_16x16x32_bf16 v[56:59], v[210:213], v[180:183], v[56:59]
	ds_read_b128 v[156:159], v197 offset:16384
	v_mfma_f32_16x16x32_bf16 v[52:55], v[214:217], v[180:183], v[52:55]
	ds_read_b128 v[160:163], v197 offset:18432
	v_mfma_f32_16x16x32_bf16 v[48:51], v[202:205], v[184:187], v[48:51]
	ds_read_b128 v[164:167], v151 offset:0
	v_mfma_f32_16x16x32_bf16 v[44:47], v[206:209], v[184:187], v[44:47]
	ds_read_b128 v[168:171], v151 offset:2048
	v_mfma_f32_16x16x32_bf16 v[40:43], v[210:213], v[184:187], v[40:43]
	ds_read_b128 v[172:175], v151 offset:4096
	v_mfma_f32_16x16x32_bf16 v[32:35], v[214:217], v[184:187], v[32:35]
	ds_read_b128 v[176:179], v151 offset:6144
	v_mfma_f32_16x16x32_bf16 v[36:39], v[202:205], v[188:191], v[36:39]
	s_add_i32 m0, s31, 0xbf80
	v_mfma_f32_16x16x32_bf16 v[28:31], v[206:209], v[188:191], v[28:31]
	global_load_lds_dwordx4 v0, s[100:101] offset:128
	v_mfma_f32_16x16x32_bf16 v[24:27], v[210:213], v[188:191], v[24:27]
	v_mfma_f32_16x16x32_bf16 v[20:23], v[214:217], v[188:191], v[20:23]
	s_add_i32 m0, s31, 0xdf80
	v_mfma_f32_16x16x32_bf16 v[16:19], v[202:205], v[192:195], v[16:19]
	global_load_lds_dwordx4 v134, s[100:101] offset:128
	v_mfma_f32_16x16x32_bf16 v[12:15], v[206:209], v[192:195], v[12:15]
	v_mfma_f32_16x16x32_bf16 v[8:11], v[210:213], v[192:195], v[8:11]
	v_mfma_f32_16x16x32_bf16 v[4:7], v[214:217], v[192:195], v[4:7]
	s_add_i32 s77, s77, 2
	s_add_u32 s75, s75, 0x100
	s_addc_u32 s76, s76, 0
	s_add_u32 s6, s6, 0x100
	s_addc_u32 s7, s7, 0
	s_cmp_gt_u32 s77, 29
	s_cbranch_scc0 .Lin_loop
	s_waitcnt lgkmcnt(0)
	s_mul_hi_u32 s6, s71, 0xaaaaaaab
	s_lshr_b32 s6, s6, 1
	s_mul_i32 s6, s6, 3
	s_sub_i32 s6, s71, s6
	s_lshl_b32 s6, s6, 10
	s_add_i32 s21, s6, 0
	s_add_i32 s21, s21, 0x20000
	v_lshl_add_u32 v144, s30, 8, v149
	s_cmp_gt_i32 s28, 51
	s_mov_b64 s[6:7], -1
	s_cbranch_scc0 .LBB0_187
	s_and_saveexec_b64 s[6:7], s[8:9]
	s_cbranch_execz .LBB0_186
;     __device__ __forceinline__ void operator()(AccT& acc, const pg8::Unit& u, int wr, int wc, int fr, int fq, const LAS float* rs) const {
;     ...
;         } else if (wc == 0 && fq == 0) {
; #pragma unroll
;             for (int ai = 0; ai < 2; ++ai)
; #pragma unroll
;                 for (int m = 0; m < 4; ++m) {
;                     const int row = row0 + ai * 128 + m * 16; const float sc = rsqrtf(rs[ai * 128 + wr * 64 + m * 16 + fr] * (1.0f / D) + EPS);
;                     *(f32x4*)(gates + (size_t)row * 8) = acc[ai][0][m][0] * sc; *(f32x4*)(gates + (size_t)row * 8 + 4) = acc[ai][0][m][1] * sc;
;                 }
	s_lshl_b32 s23, s55, 2
	s_add_i32 s23, s21, s23
	v_lshl_add_u32 v162, v148, 2, s23
	ds_read2_b32 v[146:147], v162 offset1:16
	v_ashrrev_i32_e32 v145, 31, v144
	v_lshlrev_b64 v[152:153], 5, v[144:145]
	v_lshl_add_u64 v[156:157], s[18:19], 0, v[152:153]
	s_mov_b64 s[34:35], 0x1000
	s_waitcnt lgkmcnt(0)
	v_fmamk_f32 v145, v146, 0x3a000000, v220
	v_mul_f32_e32 v146, 0x4b800000, v145
	v_cmp_gt_f32_e32 vcc, s96, v145
	v_fmamk_f32 v147, v147, 0x3a000000, v220
	v_mul_f32_e32 v158, 0x4b800000, v147
	v_cndmask_b32_e32 v145, v145, v146, vcc
	v_rsq_f32_e32 v145, v145
	s_nop 0
	v_mul_f32_e32 v146, 0x45800000, v145
	v_cndmask_b32_e32 v146, v145, v146, vcc
	v_cmp_gt_f32_e32 vcc, s96, v147
	v_pk_mul_f32 v[154:155], v[130:131], v[146:147] op_sel_hi:[1,0]
	v_pk_mul_f32 v[152:153], v[128:129], v[146:147] op_sel_hi:[1,0]
	v_cndmask_b32_e32 v145, v147, v158, vcc
	global_store_dwordx4 v[156:157], v[152:155], off
	v_rsq_f32_e32 v145, v145
	s_nop 0
	v_pk_mul_f32 v[154:155], v[126:127], v[146:147] op_sel_hi:[1,0]
	v_pk_mul_f32 v[152:153], v[124:125], v[146:147] op_sel_hi:[1,0]
	ds_read2_b32 v[146:147], v162 offset0:32 offset1:48
	global_store_dwordx4 v[156:157], v[152:155], off offset:16
	s_nop 1
	v_mul_f32_e32 v152, 0x45800000, v145
	v_cndmask_b32_e32 v158, v145, v152, vcc
	s_waitcnt lgkmcnt(0)
	v_fmamk_f32 v145, v146, 0x3a000000, v220
	v_mul_f32_e32 v146, 0x4b800000, v145
	v_cmp_gt_f32_e32 vcc, s96, v145
	v_pk_mul_f32 v[154:155], v[114:115], v[158:159] op_sel_hi:[1,0]
	v_pk_mul_f32 v[152:153], v[112:113], v[158:159] op_sel_hi:[1,0]
	v_cndmask_b32_e32 v145, v145, v146, vcc
	v_rsq_f32_e32 v145, v145
	global_store_dwordx4 v[156:157], v[152:155], off offset:512
	v_mul_f32_e32 v146, 0x45800000, v145
	s_nop 0
	v_pk_mul_f32 v[154:155], v[110:111], v[158:159] op_sel_hi:[1,0]
	v_pk_mul_f32 v[152:153], v[108:109], v[158:159] op_sel_hi:[1,0]
	v_cndmask_b32_e32 v146, v145, v146, vcc
	v_fmamk_f32 v145, v147, 0x3a000000, v220
	global_store_dwordx4 v[156:157], v[152:155], off offset:528
	v_cmp_gt_f32_e32 vcc, s96, v145
	s_nop 0
	v_pk_mul_f32 v[154:155], v[102:103], v[146:147] op_sel_hi:[1,0]
	v_pk_mul_f32 v[152:153], v[100:101], v[146:147] op_sel_hi:[1,0]
	v_mul_f32_e32 v147, 0x4b800000, v145
	v_cndmask_b32_e32 v145, v145, v147, vcc
	global_store_dwordx4 v[156:157], v[152:155], off offset:1024
	v_rsq_f32_e32 v145, v145
	s_nop 0
	v_pk_mul_f32 v[154:155], v[94:95], v[146:147] op_sel_hi:[1,0]
	v_pk_mul_f32 v[152:153], v[92:93], v[146:147] op_sel_hi:[1,0]
	ds_read2_b32 v[146:147], v162 offset0:128 offset1:144
	global_store_dwordx4 v[156:157], v[152:155], off offset:1040
	s_nop 1
	v_mul_f32_e32 v152, 0x45800000, v145
	v_cndmask_b32_e32 v158, v145, v152, vcc
	s_waitcnt lgkmcnt(0)
	v_fmamk_f32 v145, v146, 0x3a000000, v220
	v_mul_f32_e32 v146, 0x4b800000, v145
	v_cmp_gt_f32_e32 vcc, s96, v145
	v_pk_mul_f32 v[154:155], v[82:83], v[158:159] op_sel_hi:[1,0]
	v_pk_mul_f32 v[152:153], v[80:81], v[158:159] op_sel_hi:[1,0]
	v_cndmask_b32_e32 v145, v145, v146, vcc
	v_rsq_f32_e32 v145, v145
	global_store_dwordx4 v[156:157], v[152:155], off offset:1536
	v_mul_f32_e32 v146, 0x45800000, v145
	v_cndmask_b32_e32 v146, v145, v146, vcc
	v_add_co_u32_e32 v160, vcc, s94, v156
	v_pk_mul_f32 v[154:155], v[78:79], v[158:159] op_sel_hi:[1,0]
	v_pk_mul_f32 v[152:153], v[76:77], v[158:159] op_sel_hi:[1,0]
	v_addc_co_u32_e32 v161, vcc, 0, v157, vcc
	v_fmamk_f32 v145, v147, 0x3a000000, v220
	global_store_dwordx4 v[156:157], v[152:155], off offset:1552
	v_cmp_gt_f32_e32 vcc, s96, v145
	v_lshl_add_u64 v[158:159], v[156:157], 0, s[34:35]
	v_pk_mul_f32 v[154:155], v[66:67], v[146:147] op_sel_hi:[1,0]
	v_pk_mul_f32 v[152:153], v[64:65], v[146:147] op_sel_hi:[1,0]
	v_mul_f32_e32 v147, 0x4b800000, v145
	global_store_dwordx4 v[160:161], v[152:155], off
	v_cndmask_b32_e32 v145, v145, v147, vcc
	v_rsq_f32_e32 v145, v145
	v_pk_mul_f32 v[154:155], v[62:63], v[146:147] op_sel_hi:[1,0]
	v_pk_mul_f32 v[152:153], v[60:61], v[146:147] op_sel_hi:[1,0]
	global_store_dwordx4 v[158:159], v[152:155], off offset:16
	ds_read2_b32 v[158:159], v162 offset0:160 offset1:176
	v_mul_f32_e32 v146, 0x45800000, v145
	v_cndmask_b32_e32 v146, v145, v146, vcc
	v_pk_mul_f32 v[154:155], v[50:51], v[146:147] op_sel_hi:[1,0]
	v_pk_mul_f32 v[152:153], v[48:49], v[146:147] op_sel_hi:[1,0]
	s_waitcnt lgkmcnt(0)
	v_fmamk_f32 v145, v158, 0x3a000000, v220
	v_mul_f32_e32 v147, 0x4b800000, v145
	v_cmp_gt_f32_e32 vcc, s96, v145
	s_mov_b64 s[34:35], 0x1200
	global_store_dwordx4 v[160:161], v[152:155], off offset:512
	v_cndmask_b32_e32 v145, v145, v147, vcc
	v_rsq_f32_e32 v145, v145
	v_pk_mul_f32 v[154:155], v[46:47], v[146:147] op_sel_hi:[1,0]
	v_pk_mul_f32 v[152:153], v[44:45], v[146:147] op_sel_hi:[1,0]
	v_lshl_add_u64 v[162:163], v[156:157], 0, s[34:35]
	v_mul_f32_e32 v146, 0x45800000, v145
	v_cndmask_b32_e32 v146, v145, v146, vcc
	v_fmamk_f32 v145, v159, 0x3a000000, v220
	global_store_dwordx4 v[162:163], v[152:155], off offset:16
	v_cmp_gt_f32_e32 vcc, s96, v145
	s_mov_b64 s[34:35], 0x1400
	v_pk_mul_f32 v[154:155], v[38:39], v[146:147] op_sel_hi:[1,0]
	v_pk_mul_f32 v[152:153], v[36:37], v[146:147] op_sel_hi:[1,0]
	v_mul_f32_e32 v147, 0x4b800000, v145
	v_cndmask_b32_e32 v145, v145, v147, vcc
	v_rsq_f32_e32 v145, v145
	global_store_dwordx4 v[160:161], v[152:155], off offset:1024
	v_lshl_add_u64 v[162:163], v[156:157], 0, s[34:35]
	s_mov_b64 s[34:35], 0x1600
	v_pk_mul_f32 v[154:155], v[30:31], v[146:147] op_sel_hi:[1,0]
	v_pk_mul_f32 v[152:153], v[28:29], v[146:147] op_sel_hi:[1,0]
	v_mul_f32_e32 v146, 0x45800000, v145
	v_cndmask_b32_e32 v146, v145, v146, vcc
	global_store_dwordx4 v[162:163], v[152:155], off offset:16
	v_lshl_add_u64 v[156:157], v[156:157], 0, s[34:35]
	s_nop 0
	v_pk_mul_f32 v[154:155], v[18:19], v[146:147] op_sel_hi:[1,0]
	v_pk_mul_f32 v[152:153], v[16:17], v[146:147] op_sel_hi:[1,0]
	global_store_dwordx4 v[160:161], v[152:155], off offset:1536
	s_nop 1
	v_pk_mul_f32 v[154:155], v[14:15], v[146:147] op_sel_hi:[1,0]
	v_pk_mul_f32 v[152:153], v[12:13], v[146:147] op_sel_hi:[1,0]
	global_store_dwordx4 v[156:157], v[152:155], off offset:16

; #define PG8_STAGE(bufoff, gbase, voff) do { _Pragma("unroll") for (int _i = 0; _i < 2; ++_i) \
;         __builtin_amdgcn_global_load_lds((const unsigned*)((const char*)(gbase) + (voff)[_i]), (LAS unsigned*)(lds + (bufoff) + ldsw + _i * 8192), 16, 0, 0); } while (0)
; #define PG8_LDA(dst, b, h) do { _Pragma("unroll") for (int m = 0; m < 4; ++m) _Pragma("unroll") for (int k = 0; k < 2; ++k) dst[m][k] = *(const LAS bf16x8*)(lds + PG8_SA(b, h) + aoff + m * 2048 + k * 1024); } while (0)
; #define PG8_LDB(dst, b, h) do { _Pragma("unroll") for (int n = 0; n < 2; ++n) _Pragma("unroll") for (int k = 0; k < 2; ++k) dst[n][k] = *(const LAS bf16x8*)(lds + PG8_SB(b, h) + boff + n * 2048 + k * 1024); } while (0)
; #define PG8_MMA(ai, bj, At, Bt) do { __builtin_amdgcn_s_setprio(1); _Pragma("unroll") for (int m = 0; m < 4; ++m) _Pragma("unroll") for (int n = 0; n < 2; ++n) _Pragma("unroll") for (int k = 0; k < 2; ++k) \
;         acc[ai][bj][m][n] = __builtin_amdgcn_mfma_f32_16x16x32_bf16(Bt[n][k], At[m][k], acc[ai][bj][m][n], 0, 0, 0); __builtin_amdgcn_s_setprio(0); } while (0)
; #define PG8_WAIT_V(n) asm volatile("s_waitcnt vmcnt(" #n ")" ::: "memory")
; #define PG8_WAIT_L(n) asm volatile("s_waitcnt lgkmcnt(" #n ")" ::: "memory")
; template <class Epi, int LDA, int LDB, int KK>
; __device__ __forceinline__ void gemm_phase(int wv, LAS unsigned char* lds, const Gemm g, const StaticOrder& S, const Epi& E) {
;     ...
;           for (; t < tend; t += 2) {
;             const bool last = (t == nt - 2);
;             const char* a1 = cA + (size_t)(t + 1) * kstep;
;             const char* a2 = last ? nA : cA + (size_t)(t + 2) * kstep; const char* b2 = last ? nB : cB + (size_t)(t + 2) * kstep;
;             const char* a3 = a2 + kstep; const char* b3 = b2 + kstep;
;             PG8_LDB(B0, 0, 0); PG8_SCHED; PG8_LDA(At, 0, 0); PG8_STAGE(PG8_SA(1, 1), a1 + hstepA, voffA);
;             PG8_WAIT_L(8); PG8_BAR; PG8_WAIT_L(0); PG8_MMA(0, 0, At, B0); PG8_BAR; PG8_SCHED;
;             PG8_LDB(B1, 0, 1); PG8_STAGE(PG8_SB(0, 0), b2, voffB);
;             PG8_BAR; PG8_WAIT_L(0); PG8_MMA(0, 1, At, B1); PG8_BAR;
;             PG8_LDA(At, 0, 1); PG8_STAGE(PG8_SA(0, 0), a2, voffA);
;             PG8_BAR; PG8_WAIT_L(0); PG8_MMA(1, 0, At, B0); PG8_BAR; PG8_SCHED;
;             PG8_STAGE(PG8_SB(0, 1), b2 + hstepB, voffB);
;             PG8_WAIT_V(6); PG8_BAR; PG8_MMA(1, 1, At, B1); PG8_BAR;
.Lmerge_loop:
	s_mov_b32 s26, s22
	s_add_i32 s22, s22, 2
	s_cmp_eq_u32 s26, 30
	s_cselect_b32 s27, s15, s56
	s_cselect_b32 s26, s43, s55
	s_cselect_b32 s25, s13, s47
	s_cselect_b32 s24, s44, s23
	s_waitcnt lgkmcnt(0)
	v_mfma_f32_16x16x32_bf16 v[128:131], v[132:135], v[148:151], v[128:131]
	ds_read_b128 v[180:183], v0 offset:1024
	v_mfma_f32_16x16x32_bf16 v[124:127], v[136:139], v[148:151], v[124:127]
	ds_read_b128 v[184:187], v0 offset:3072
	v_mfma_f32_16x16x32_bf16 v[120:123], v[140:143], v[148:151], v[120:123]
	ds_read_b128 v[188:191], v0 offset:17408
	v_mfma_f32_16x16x32_bf16 v[116:119], v[144:147], v[148:151], v[116:119]
	ds_read_b128 v[192:195], v0 offset:19456
	v_mfma_f32_16x16x32_bf16 v[112:115], v[132:135], v[152:155], v[112:115]
	ds_read_b128 v[164:167], v218 offset:1024
	v_mfma_f32_16x16x32_bf16 v[108:111], v[136:139], v[152:155], v[108:111]
	ds_read_b128 v[168:171], v218 offset:3072
	v_mfma_f32_16x16x32_bf16 v[104:107], v[140:143], v[152:155], v[104:107]
	ds_read_b128 v[172:175], v218 offset:5120
	v_mfma_f32_16x16x32_bf16 v[100:103], v[144:147], v[152:155], v[100:103]
	ds_read_b128 v[176:179], v218 offset:7168
	v_mfma_f32_16x16x32_bf16 v[96:99], v[132:135], v[156:159], v[96:99]
	v_mfma_f32_16x16x32_bf16 v[92:95], v[136:139], v[156:159], v[92:95]
	v_mfma_f32_16x16x32_bf16 v[88:91], v[140:143], v[156:159], v[88:91]
	v_mfma_f32_16x16x32_bf16 v[84:87], v[144:147], v[156:159], v[84:87]
	v_mfma_f32_16x16x32_bf16 v[80:83], v[132:135], v[160:163], v[80:83]
	v_mfma_f32_16x16x32_bf16 v[76:79], v[136:139], v[160:163], v[76:79]
	v_mfma_f32_16x16x32_bf16 v[72:75], v[140:143], v[160:163], v[72:75]
	v_mfma_f32_16x16x32_bf16 v[68:71], v[144:147], v[160:163], v[68:71]
	s_waitcnt vmcnt(8) lgkmcnt(0)
	s_barrier
	v_mfma_f32_16x16x32_bf16 v[128:131], v[180:183], v[164:167], v[128:131]
	ds_read_b128 v[148:151], v218 offset:16384
	v_mfma_f32_16x16x32_bf16 v[124:127], v[184:187], v[164:167], v[124:127]
	ds_read_b128 v[152:155], v218 offset:18432
	v_mfma_f32_16x16x32_bf16 v[120:123], v[188:191], v[164:167], v[120:123]
	ds_read_b128 v[156:159], v218 offset:20480
	v_mfma_f32_16x16x32_bf16 v[116:119], v[192:195], v[164:167], v[116:119]
	ds_read_b128 v[160:163], v218 offset:22528
	v_mfma_f32_16x16x32_bf16 v[112:115], v[180:183], v[168:171], v[112:115]
	s_add_i32 m0, s36, 0x10000
	v_mfma_f32_16x16x32_bf16 v[108:111], v[184:187], v[168:171], v[108:111]
	global_load_lds_dwordx4 v206, s[24:25]
	v_mfma_f32_16x16x32_bf16 v[104:107], v[188:191], v[168:171], v[104:107]
	v_mfma_f32_16x16x32_bf16 v[100:103], v[192:195], v[168:171], v[100:103]
	s_add_i32 m0, s36, 0x12000
	v_mfma_f32_16x16x32_bf16 v[96:99], v[180:183], v[172:175], v[96:99]
	global_load_lds_dwordx4 v202, s[24:25]
	v_mfma_f32_16x16x32_bf16 v[92:95], v[184:187], v[172:175], v[92:95]
	v_mfma_f32_16x16x32_bf16 v[88:91], v[188:191], v[172:175], v[88:91]
	s_mov_b32 m0, s36
	v_mfma_f32_16x16x32_bf16 v[84:87], v[192:195], v[172:175], v[84:87]
	global_load_lds_dwordx4 v208, s[26:27]
	v_mfma_f32_16x16x32_bf16 v[80:83], v[180:183], v[176:179], v[80:83]
	v_mfma_f32_16x16x32_bf16 v[76:79], v[184:187], v[176:179], v[76:79]
	v_mfma_f32_16x16x32_bf16 v[72:75], v[188:191], v[176:179], v[72:75]
	v_mfma_f32_16x16x32_bf16 v[68:71], v[192:195], v[176:179], v[68:71]
	s_waitcnt lgkmcnt(0)
	v_mfma_f32_16x16x32_bf16 v[64:67], v[132:135], v[148:151], v[64:67]
	ds_read_b128 v[164:167], v218 offset:17408
	v_mfma_f32_16x16x32_bf16 v[60:63], v[136:139], v[148:151], v[60:63]
	ds_read_b128 v[168:171], v218 offset:19456
	v_mfma_f32_16x16x32_bf16 v[56:59], v[140:143], v[148:151], v[56:59]
	ds_read_b128 v[172:175], v218 offset:21504
	v_mfma_f32_16x16x32_bf16 v[52:55], v[144:147], v[148:151], v[52:55]
	ds_read_b128 v[176:179], v218 offset:23552
	v_mfma_f32_16x16x32_bf16 v[48:51], v[132:135], v[152:155], v[48:51]
	s_add_i32 m0, s36, 0x2000
	v_mfma_f32_16x16x32_bf16 v[44:47], v[136:139], v[152:155], v[44:47]
	global_load_lds_dwordx4 v204, s[26:27]
	v_mfma_f32_16x16x32_bf16 v[40:43], v[140:143], v[152:155], v[40:43]
	v_mfma_f32_16x16x32_bf16 v[36:39], v[144:147], v[152:155], v[36:39]
	s_add_u32 s98, s24, 0x80000
	s_addc_u32 s99, s25, 0
	s_add_i32 m0, s36, 0x14000
	v_mfma_f32_16x16x32_bf16 v[32:35], v[132:135], v[156:159], v[32:35]
	global_load_lds_dwordx4 v206, s[98:99]
	v_mfma_f32_16x16x32_bf16 v[28:31], v[136:139], v[156:159], v[28:31]
	v_mfma_f32_16x16x32_bf16 v[24:27], v[140:143], v[156:159], v[24:27]
	s_add_i32 m0, s36, 0x16000
	v_mfma_f32_16x16x32_bf16 v[20:23], v[144:147], v[156:159], v[20:23]
	global_load_lds_dwordx4 v202, s[98:99]
	v_mfma_f32_16x16x32_bf16 v[16:19], v[132:135], v[160:163], v[16:19]
	v_mfma_f32_16x16x32_bf16 v[12:15], v[136:139], v[160:163], v[12:15]
	v_mfma_f32_16x16x32_bf16 v[8:11], v[140:143], v[160:163], v[8:11]
	v_mfma_f32_16x16x32_bf16 v[4:7], v[144:147], v[160:163], v[4:7]
	s_waitcnt vmcnt(8) lgkmcnt(0)
	s_barrier
; #define PG8_STAGE(bufoff, gbase, voff) do { _Pragma("unroll") for (int _i = 0; _i < 2; ++_i) \
;         __builtin_amdgcn_global_load_lds((const unsigned*)((const char*)(gbase) + (voff)[_i]), (LAS unsigned*)(lds + (bufoff) + ldsw + _i * 8192), 16, 0, 0); } while (0)
; #define PG8_LDA(dst, b, h) do { _Pragma("unroll") for (int m = 0; m < 4; ++m) _Pragma("unroll") for (int k = 0; k < 2; ++k) dst[m][k] = *(const LAS bf16x8*)(lds + PG8_SA(b, h) + aoff + m * 2048 + k * 1024); } while (0)
; #define PG8_LDB(dst, b, h) do { _Pragma("unroll") for (int n = 0; n < 2; ++n) _Pragma("unroll") for (int k = 0; k < 2; ++k) dst[n][k] = *(const LAS bf16x8*)(lds + PG8_SB(b, h) + boff + n * 2048 + k * 1024); } while (0)
; #define PG8_MMA(ai, bj, At, Bt) do { __builtin_amdgcn_s_setprio(1); _Pragma("unroll") for (int m = 0; m < 4; ++m) _Pragma("unroll") for (int n = 0; n < 2; ++n) _Pragma("unroll") for (int k = 0; k < 2; ++k) \
;         acc[ai][bj][m][n] = __builtin_amdgcn_mfma_f32_16x16x32_bf16(Bt[n][k], At[m][k], acc[ai][bj][m][n], 0, 0, 0); __builtin_amdgcn_s_setprio(0); } while (0)
; #define PG8_WAIT_L(n) asm volatile("s_waitcnt lgkmcnt(" #n ")" ::: "memory")
; #define PG8_BAR __builtin_amdgcn_s_barrier()
; #define PG8_SCHED __builtin_amdgcn_sched_barrier(0)
; template <class Epi, int LDA, int LDB, int KK>
; __device__ __forceinline__ void gemm_phase(int wv, LAS unsigned char* lds, const Gemm g, const StaticOrder& S, const Epi& E) {
;     ...
;             PG8_LDB(B0, 1, 0); PG8_SCHED; PG8_LDA(At, 1, 0); PG8_STAGE(PG8_SA(0, 1), a2 + hstepA, voffA);
;             PG8_WAIT_L(8); PG8_BAR; PG8_WAIT_L(0); PG8_MMA(0, 0, At, B0); PG8_BAR; PG8_SCHED;
;             PG8_LDB(B1, 1, 1); PG8_STAGE(PG8_SB(1, 0), b3, voffB);
;             PG8_BAR; PG8_WAIT_L(0); PG8_MMA(0, 1, At, B1); PG8_BAR;
	v_mfma_f32_16x16x32_bf16 v[64:67], v[180:183], v[164:167], v[64:67]
	ds_read_b128 v[132:135], v0 offset:32768
	v_mfma_f32_16x16x32_bf16 v[60:63], v[184:187], v[164:167], v[60:63]
	ds_read_b128 v[136:139], v0 offset:34816
	v_mfma_f32_16x16x32_bf16 v[56:59], v[188:191], v[164:167], v[56:59]
	ds_read_b128 v[140:143], v0 offset:49152
	v_mfma_f32_16x16x32_bf16 v[52:55], v[192:195], v[164:167], v[52:55]
	ds_read_b128 v[144:147], v0 offset:51200
	v_mfma_f32_16x16x32_bf16 v[48:51], v[180:183], v[168:171], v[48:51]
	ds_read_b128 v[148:151], v218 offset:32768
	v_mfma_f32_16x16x32_bf16 v[44:47], v[184:187], v[168:171], v[44:47]
	ds_read_b128 v[152:155], v218 offset:34816
	v_mfma_f32_16x16x32_bf16 v[40:43], v[188:191], v[168:171], v[40:43]
	ds_read_b128 v[156:159], v218 offset:36864
	v_mfma_f32_16x16x32_bf16 v[36:39], v[192:195], v[168:171], v[36:39]
	ds_read_b128 v[160:163], v218 offset:38912
	v_mfma_f32_16x16x32_bf16 v[32:35], v[180:183], v[172:175], v[32:35]
	s_add_u32 s98, s26, 0x80000
	s_addc_u32 s99, s27, 0
	s_add_i32 m0, s36, 0x4000
	v_mfma_f32_16x16x32_bf16 v[28:31], v[184:187], v[172:175], v[28:31]
	global_load_lds_dwordx4 v208, s[98:99]
	v_mfma_f32_16x16x32_bf16 v[24:27], v[188:191], v[172:175], v[24:27]
	v_mfma_f32_16x16x32_bf16 v[20:23], v[192:195], v[172:175], v[20:23]
	s_add_i32 m0, s36, 0x6000
	v_mfma_f32_16x16x32_bf16 v[16:19], v[180:183], v[176:179], v[16:19]
	global_load_lds_dwordx4 v204, s[98:99]
	v_mfma_f32_16x16x32_bf16 v[12:15], v[184:187], v[176:179], v[12:15]
	v_mfma_f32_16x16x32_bf16 v[8:11], v[188:191], v[176:179], v[8:11]
	v_mfma_f32_16x16x32_bf16 v[4:7], v[192:195], v[176:179], v[4:7]
	s_waitcnt lgkmcnt(0)
	v_mfma_f32_16x16x32_bf16 v[128:131], v[132:135], v[148:151], v[128:131]
	ds_read_b128 v[180:183], v0 offset:33792
	v_mfma_f32_16x16x32_bf16 v[124:127], v[136:139], v[148:151], v[124:127]
	ds_read_b128 v[184:187], v0 offset:35840
	v_mfma_f32_16x16x32_bf16 v[120:123], v[140:143], v[148:151], v[120:123]
	ds_read_b128 v[188:191], v0 offset:50176
	v_mfma_f32_16x16x32_bf16 v[116:119], v[144:147], v[148:151], v[116:119]
	ds_read_b128 v[192:195], v0 offset:52224
	v_mfma_f32_16x16x32_bf16 v[112:115], v[132:135], v[152:155], v[112:115]
	ds_read_b128 v[164:167], v218 offset:33792
	v_mfma_f32_16x16x32_bf16 v[108:111], v[136:139], v[152:155], v[108:111]
	ds_read_b128 v[168:171], v218 offset:35840
	v_mfma_f32_16x16x32_bf16 v[104:107], v[140:143], v[152:155], v[104:107]
	ds_read_b128 v[172:175], v218 offset:37888
	v_mfma_f32_16x16x32_bf16 v[100:103], v[144:147], v[152:155], v[100:103]
	ds_read_b128 v[176:179], v218 offset:39936
	v_mfma_f32_16x16x32_bf16 v[96:99], v[132:135], v[156:159], v[96:99]
	v_mfma_f32_16x16x32_bf16 v[92:95], v[136:139], v[156:159], v[92:95]
	v_mfma_f32_16x16x32_bf16 v[88:91], v[140:143], v[156:159], v[88:91]
	v_mfma_f32_16x16x32_bf16 v[84:87], v[144:147], v[156:159], v[84:87]
	v_mfma_f32_16x16x32_bf16 v[80:83], v[132:135], v[160:163], v[80:83]
	v_mfma_f32_16x16x32_bf16 v[76:79], v[136:139], v[160:163], v[76:79]
	v_mfma_f32_16x16x32_bf16 v[72:75], v[140:143], v[160:163], v[72:75]
	v_mfma_f32_16x16x32_bf16 v[68:71], v[144:147], v[160:163], v[68:71]
	s_waitcnt vmcnt(8) lgkmcnt(0)
	s_barrier
; #define PG8_STAGE(bufoff, gbase, voff) do { _Pragma("unroll") for (int _i = 0; _i < 2; ++_i) \
;         __builtin_amdgcn_global_load_lds((const unsigned*)((const char*)(gbase) + (voff)[_i]), (LAS unsigned*)(lds + (bufoff) + ldsw + _i * 8192), 16, 0, 0); } while (0)
; #define PG8_LDA(dst, b, h) do { _Pragma("unroll") for (int m = 0; m < 4; ++m) _Pragma("unroll") for (int k = 0; k < 2; ++k) dst[m][k] = *(const LAS bf16x8*)(lds + PG8_SA(b, h) + aoff + m * 2048 + k * 1024); } while (0)
; #define PG8_LDB(dst, b, h) do { _Pragma("unroll") for (int n = 0; n < 2; ++n) _Pragma("unroll") for (int k = 0; k < 2; ++k) dst[n][k] = *(const LAS bf16x8*)(lds + PG8_SB(b, h) + boff + n * 2048 + k * 1024); } while (0)
; #define PG8_MMA(ai, bj, At, Bt) do { __builtin_amdgcn_s_setprio(1); _Pragma("unroll") for (int m = 0; m < 4; ++m) _Pragma("unroll") for (int n = 0; n < 2; ++n) _Pragma("unroll") for (int k = 0; k < 2; ++k) \
;         acc[ai][bj][m][n] = __builtin_amdgcn_mfma_f32_16x16x32_bf16(Bt[n][k], At[m][k], acc[ai][bj][m][n], 0, 0, 0); __builtin_amdgcn_s_setprio(0); } while (0)
; #define PG8_WAIT_V(n) asm volatile("s_waitcnt vmcnt(" #n ")" ::: "memory")
; #define PG8_WAIT_L(n) asm volatile("s_waitcnt lgkmcnt(" #n ")" ::: "memory")
; #define PG8_BAR __builtin_amdgcn_s_barrier()
; #define PG8_SCHED __builtin_amdgcn_sched_barrier(0)
; template <class Epi, int LDA, int LDB, int KK>
; __device__ __forceinline__ void gemm_phase(int wv, LAS unsigned char* lds, const Gemm g, const StaticOrder& S, const Epi& E) {
;     ...
;             PG8_LDB(B0, 1, 0); PG8_SCHED; PG8_LDA(At, 1, 0); PG8_STAGE(PG8_SA(0, 1), a2 + hstepA, voffA);
;             PG8_WAIT_L(8); PG8_BAR; PG8_WAIT_L(0); PG8_MMA(0, 0, At, B0); PG8_BAR; PG8_SCHED;
;             PG8_LDB(B1, 1, 1); PG8_STAGE(PG8_SB(1, 0), b3, voffB);
;             PG8_BAR; PG8_WAIT_L(0); PG8_MMA(0, 1, At, B1); PG8_BAR;
;             PG8_LDA(At, 1, 1); PG8_STAGE(PG8_SA(1, 0), a3, voffA);
;             PG8_BAR; PG8_WAIT_L(0); PG8_MMA(1, 0, At, B0); PG8_BAR; PG8_SCHED;
;             PG8_STAGE(PG8_SB(1, 1), b3 + hstepB, voffB);
;             PG8_WAIT_V(6); PG8_BAR; PG8_MMA(1, 1, At, B1); PG8_BAR;
	v_mfma_f32_16x16x32_bf16 v[128:131], v[180:183], v[164:167], v[128:131]
	ds_read_b128 v[148:151], v218 offset:49152
	v_mfma_f32_16x16x32_bf16 v[124:127], v[184:187], v[164:167], v[124:127]
	ds_read_b128 v[152:155], v218 offset:51200
	v_mfma_f32_16x16x32_bf16 v[120:123], v[188:191], v[164:167], v[120:123]
	ds_read_b128 v[156:159], v218 offset:53248
	v_mfma_f32_16x16x32_bf16 v[116:119], v[192:195], v[164:167], v[116:119]
	ds_read_b128 v[160:163], v218 offset:55296
	v_mfma_f32_16x16x32_bf16 v[112:115], v[180:183], v[168:171], v[112:115]
	s_add_i32 m0, s36, 0x17f80
	v_mfma_f32_16x16x32_bf16 v[108:111], v[184:187], v[168:171], v[108:111]
	global_load_lds_dwordx4 v206, s[24:25] offset:128
	v_mfma_f32_16x16x32_bf16 v[104:107], v[188:191], v[168:171], v[104:107]
	v_mfma_f32_16x16x32_bf16 v[100:103], v[192:195], v[168:171], v[100:103]
	s_add_i32 m0, s36, 0x19f80
	v_mfma_f32_16x16x32_bf16 v[96:99], v[180:183], v[172:175], v[96:99]
	global_load_lds_dwordx4 v202, s[24:25] offset:128
	v_mfma_f32_16x16x32_bf16 v[92:95], v[184:187], v[172:175], v[92:95]
	v_mfma_f32_16x16x32_bf16 v[88:91], v[188:191], v[172:175], v[88:91]
	s_add_i32 m0, s36, 0x7f80
	v_mfma_f32_16x16x32_bf16 v[84:87], v[192:195], v[172:175], v[84:87]
	global_load_lds_dwordx4 v208, s[26:27] offset:128
	v_mfma_f32_16x16x32_bf16 v[80:83], v[180:183], v[176:179], v[80:83]
	v_mfma_f32_16x16x32_bf16 v[76:79], v[184:187], v[176:179], v[76:79]
	v_mfma_f32_16x16x32_bf16 v[72:75], v[188:191], v[176:179], v[72:75]
	v_mfma_f32_16x16x32_bf16 v[68:71], v[192:195], v[176:179], v[68:71]
	s_waitcnt lgkmcnt(0)
	v_mfma_f32_16x16x32_bf16 v[64:67], v[132:135], v[148:151], v[64:67]
	ds_read_b128 v[164:167], v218 offset:50176
	v_mfma_f32_16x16x32_bf16 v[60:63], v[136:139], v[148:151], v[60:63]
	ds_read_b128 v[168:171], v218 offset:52224
	v_mfma_f32_16x16x32_bf16 v[56:59], v[140:143], v[148:151], v[56:59]
	ds_read_b128 v[172:175], v218 offset:54272
	v_mfma_f32_16x16x32_bf16 v[52:55], v[144:147], v[148:151], v[52:55]
	ds_read_b128 v[176:179], v218 offset:56320
	v_mfma_f32_16x16x32_bf16 v[48:51], v[132:135], v[152:155], v[48:51]
	s_add_i32 m0, s36, 0x9f80
	v_mfma_f32_16x16x32_bf16 v[44:47], v[136:139], v[152:155], v[44:47]
	global_load_lds_dwordx4 v204, s[26:27] offset:128
	v_mfma_f32_16x16x32_bf16 v[40:43], v[140:143], v[152:155], v[40:43]
	v_mfma_f32_16x16x32_bf16 v[36:39], v[144:147], v[152:155], v[36:39]
	s_add_u32 s98, s24, 0x80000
	s_addc_u32 s99, s25, 0
	s_add_i32 m0, s36, 0x1bf80
	v_mfma_f32_16x16x32_bf16 v[32:35], v[132:135], v[156:159], v[32:35]
	global_load_lds_dwordx4 v206, s[98:99] offset:128
	v_mfma_f32_16x16x32_bf16 v[28:31], v[136:139], v[156:159], v[28:31]
	v_mfma_f32_16x16x32_bf16 v[24:27], v[140:143], v[156:159], v[24:27]
	s_add_i32 m0, s36, 0x1df80
	v_mfma_f32_16x16x32_bf16 v[20:23], v[144:147], v[156:159], v[20:23]
	global_load_lds_dwordx4 v202, s[98:99] offset:128
	v_mfma_f32_16x16x32_bf16 v[16:19], v[132:135], v[160:163], v[16:19]
	v_mfma_f32_16x16x32_bf16 v[12:15], v[136:139], v[160:163], v[12:15]
	v_mfma_f32_16x16x32_bf16 v[8:11], v[140:143], v[160:163], v[8:11]
	v_mfma_f32_16x16x32_bf16 v[4:7], v[144:147], v[160:163], v[4:7]
	s_waitcnt vmcnt(8) lgkmcnt(0)
	s_barrier
	v_mfma_f32_16x16x32_bf16 v[64:67], v[180:183], v[164:167], v[64:67]
	ds_read_b128 v[132:135], v0 offset:0
	v_mfma_f32_16x16x32_bf16 v[60:63], v[184:187], v[164:167], v[60:63]
	ds_read_b128 v[136:139], v0 offset:2048
	v_mfma_f32_16x16x32_bf16 v[56:59], v[188:191], v[164:167], v[56:59]
	ds_read_b128 v[140:143], v0 offset:16384
	v_mfma_f32_16x16x32_bf16 v[52:55], v[192:195], v[164:167], v[52:55]
	ds_read_b128 v[144:147], v0 offset:18432
	v_mfma_f32_16x16x32_bf16 v[48:51], v[180:183], v[168:171], v[48:51]
	ds_read_b128 v[148:151], v218 offset:0
	v_mfma_f32_16x16x32_bf16 v[44:47], v[184:187], v[168:171], v[44:47]
	ds_read_b128 v[152:155], v218 offset:2048
	v_mfma_f32_16x16x32_bf16 v[40:43], v[188:191], v[168:171], v[40:43]
	ds_read_b128 v[156:159], v218 offset:4096
	v_mfma_f32_16x16x32_bf16 v[36:39], v[192:195], v[168:171], v[36:39]
	ds_read_b128 v[160:163], v218 offset:6144
	v_mfma_f32_16x16x32_bf16 v[32:35], v[180:183], v[172:175], v[32:35]
	s_add_u32 s98, s26, 0x80000
	s_addc_u32 s99, s27, 0
	s_add_i32 m0, s36, 0xbf80
	v_mfma_f32_16x16x32_bf16 v[28:31], v[184:187], v[172:175], v[28:31]
	global_load_lds_dwordx4 v208, s[98:99] offset:128
	v_mfma_f32_16x16x32_bf16 v[24:27], v[188:191], v[172:175], v[24:27]
	v_mfma_f32_16x16x32_bf16 v[20:23], v[192:195], v[172:175], v[20:23]
	s_add_i32 m0, s36, 0xdf80
	v_mfma_f32_16x16x32_bf16 v[16:19], v[180:183], v[176:179], v[16:19]
	global_load_lds_dwordx4 v204, s[98:99] offset:128
	v_mfma_f32_16x16x32_bf16 v[12:15], v[184:187], v[176:179], v[12:15]
	v_mfma_f32_16x16x32_bf16 v[8:11], v[188:191], v[176:179], v[8:11]
	v_mfma_f32_16x16x32_bf16 v[4:7], v[192:195], v[176:179], v[4:7]
	s_add_u32 s23, s23, 0x100
	s_addc_u32 s47, s47, 0
	s_add_u32 s55, s55, 0x100
	s_addc_u32 s56, s56, 0
	s_cmp_lt_i32 s22, s46
	s_cbranch_scc1 .Lmerge_loop
	s_waitcnt lgkmcnt(0)

; #define PG8_STAGE(bufoff, gbase, voff) do { _Pragma("unroll") for (int _i = 0; _i < 2; ++_i) \
;         __builtin_amdgcn_global_load_lds((const unsigned*)((const char*)(gbase) + (voff)[_i]), (LAS unsigned*)(lds + (bufoff) + ldsw + _i * 8192), 16, 0, 0); } while (0)
; #define PG8_LDA(dst, b, h) do { _Pragma("unroll") for (int m = 0; m < 4; ++m) _Pragma("unroll") for (int k = 0; k < 2; ++k) dst[m][k] = *(const LAS bf16x8*)(lds + PG8_SA(b, h) + aoff + m * 2048 + k * 1024); } while (0)
; #define PG8_LDB(dst, b, h) do { _Pragma("unroll") for (int n = 0; n < 2; ++n) _Pragma("unroll") for (int k = 0; k < 2; ++k) dst[n][k] = *(const LAS bf16x8*)(lds + PG8_SB(b, h) + boff + n * 2048 + k * 1024); } while (0)
; #define PG8_MMA(ai, bj, At, Bt) do { __builtin_amdgcn_s_setprio(1); _Pragma("unroll") for (int m = 0; m < 4; ++m) _Pragma("unroll") for (int n = 0; n < 2; ++n) _Pragma("unroll") for (int k = 0; k < 2; ++k) \
;         acc[ai][bj][m][n] = __builtin_amdgcn_mfma_f32_16x16x32_bf16(Bt[n][k], At[m][k], acc[ai][bj][m][n], 0, 0, 0); __builtin_amdgcn_s_setprio(0); } while (0)
; #define PG8_WAIT_V(n) asm volatile("s_waitcnt vmcnt(" #n ")" ::: "memory")
; #define PG8_WAIT_L(n) asm volatile("s_waitcnt lgkmcnt(" #n ")" ::: "memory")
; template <class Epi, int LDA, int LDB, int KK>
; __device__ __forceinline__ void gemm_phase(int wv, LAS unsigned char* lds, const Gemm g, const StaticOrder& S, const Epi& E) {
;     ...
;           for (; t < tend; t += 2) {
;             const bool last = (t == nt - 2);
;             const char* a1 = cA + (size_t)(t + 1) * kstep;
;             const char* a2 = last ? nA : cA + (size_t)(t + 2) * kstep; const char* b2 = last ? nB : cB + (size_t)(t + 2) * kstep;
;             const char* a3 = a2 + kstep; const char* b3 = b2 + kstep;
;             PG8_LDB(B0, 0, 0); PG8_SCHED; PG8_LDA(At, 0, 0); PG8_STAGE(PG8_SA(1, 1), a1 + hstepA, voffA);
;             PG8_WAIT_L(8); PG8_BAR; PG8_WAIT_L(0); PG8_MMA(0, 0, At, B0); PG8_BAR; PG8_SCHED;
;             PG8_LDB(B1, 0, 1); PG8_STAGE(PG8_SB(0, 0), b2, voffB);
;             PG8_BAR; PG8_WAIT_L(0); PG8_MMA(0, 1, At, B1); PG8_BAR;
;             PG8_LDA(At, 0, 1); PG8_STAGE(PG8_SA(0, 0), a2, voffA);
;             PG8_BAR; PG8_WAIT_L(0); PG8_MMA(1, 0, At, B0); PG8_BAR; PG8_SCHED;
;             PG8_STAGE(PG8_SB(0, 1), b2 + hstepB, voffB);
;             PG8_WAIT_V(6); PG8_BAR; PG8_MMA(1, 1, At, B1); PG8_BAR;
.Lout_loop:
	s_add_u32 s26, s24, 0xfff80080
	s_addc_u32 s27, s25, -1
	s_cmp_eq_u32 s69, 28
	s_cselect_b32 s29, s17, s27
	s_cselect_b32 s28, s47, s26
	s_cselect_b32 s27, s15, s68
	s_cselect_b32 s26, s55, s56
	s_waitcnt lgkmcnt(0)
	v_mfma_f32_16x16x32_bf16 v[128:131], v[132:135], v[148:151], v[128:131]
	ds_read_b128 v[202:205], v180 offset:1024
	v_mfma_f32_16x16x32_bf16 v[124:127], v[136:139], v[148:151], v[124:127]
	ds_read_b128 v[206:209], v180 offset:3072
	v_mfma_f32_16x16x32_bf16 v[120:123], v[140:143], v[148:151], v[120:123]
	ds_read_b128 v[210:213], v180 offset:17408
	v_mfma_f32_16x16x32_bf16 v[116:119], v[144:147], v[148:151], v[116:119]
	ds_read_b128 v[214:217], v180 offset:19456
	v_mfma_f32_16x16x32_bf16 v[112:115], v[132:135], v[152:155], v[112:115]
	ds_read_b128 v[164:167], v234 offset:1024
	v_mfma_f32_16x16x32_bf16 v[108:111], v[136:139], v[152:155], v[108:111]
	ds_read_b128 v[168:171], v234 offset:3072
	v_mfma_f32_16x16x32_bf16 v[104:107], v[140:143], v[152:155], v[104:107]
	ds_read_b128 v[172:175], v234 offset:5120
	v_mfma_f32_16x16x32_bf16 v[100:103], v[144:147], v[152:155], v[100:103]
	ds_read_b128 v[176:179], v234 offset:7168
	v_mfma_f32_16x16x32_bf16 v[96:99], v[132:135], v[156:159], v[96:99]
	v_mfma_f32_16x16x32_bf16 v[92:95], v[136:139], v[156:159], v[92:95]
	v_mfma_f32_16x16x32_bf16 v[88:91], v[140:143], v[156:159], v[88:91]
	v_mfma_f32_16x16x32_bf16 v[84:87], v[144:147], v[156:159], v[84:87]
	v_mfma_f32_16x16x32_bf16 v[80:83], v[132:135], v[160:163], v[80:83]
	v_mfma_f32_16x16x32_bf16 v[76:79], v[136:139], v[160:163], v[76:79]
	v_mfma_f32_16x16x32_bf16 v[72:75], v[140:143], v[160:163], v[72:75]
	v_mfma_f32_16x16x32_bf16 v[68:71], v[144:147], v[160:163], v[68:71]
	s_waitcnt vmcnt(8) lgkmcnt(0)
	s_barrier
	v_mfma_f32_16x16x32_bf16 v[128:131], v[202:205], v[164:167], v[128:131]
	ds_read_b128 v[148:151], v234 offset:16384
	v_mfma_f32_16x16x32_bf16 v[124:127], v[206:209], v[164:167], v[124:127]
	ds_read_b128 v[152:155], v234 offset:18432
	v_mfma_f32_16x16x32_bf16 v[120:123], v[210:213], v[164:167], v[120:123]
	ds_read_b128 v[156:159], v234 offset:20480
	v_mfma_f32_16x16x32_bf16 v[116:119], v[214:217], v[164:167], v[116:119]
	ds_read_b128 v[160:163], v234 offset:22528
	v_mfma_f32_16x16x32_bf16 v[112:115], v[202:205], v[168:171], v[112:115]
	s_add_i32 m0, s40, 0x10000
	v_mfma_f32_16x16x32_bf16 v[108:111], v[206:209], v[168:171], v[108:111]
	global_load_lds_dwordx4 v2, s[26:27]
	v_mfma_f32_16x16x32_bf16 v[104:107], v[210:213], v[168:171], v[104:107]
	v_mfma_f32_16x16x32_bf16 v[100:103], v[214:217], v[168:171], v[100:103]
	s_add_i32 m0, s40, 0x12000
	v_mfma_f32_16x16x32_bf16 v[96:99], v[202:205], v[172:175], v[96:99]
	global_load_lds_dwordx4 v0, s[26:27]
	v_mfma_f32_16x16x32_bf16 v[92:95], v[206:209], v[172:175], v[92:95]
	v_mfma_f32_16x16x32_bf16 v[88:91], v[210:213], v[172:175], v[88:91]
	s_mov_b32 m0, s40
	v_mfma_f32_16x16x32_bf16 v[84:87], v[214:217], v[172:175], v[84:87]
	global_load_lds_dwordx4 v190, s[28:29]
	v_mfma_f32_16x16x32_bf16 v[80:83], v[202:205], v[176:179], v[80:83]
	v_mfma_f32_16x16x32_bf16 v[76:79], v[206:209], v[176:179], v[76:79]
	v_mfma_f32_16x16x32_bf16 v[72:75], v[210:213], v[176:179], v[72:75]
	v_mfma_f32_16x16x32_bf16 v[68:71], v[214:217], v[176:179], v[68:71]
	s_waitcnt lgkmcnt(0)
	v_mfma_f32_16x16x32_bf16 v[64:67], v[132:135], v[148:151], v[64:67]
	ds_read_b128 v[164:167], v234 offset:17408
	v_mfma_f32_16x16x32_bf16 v[60:63], v[136:139], v[148:151], v[60:63]
	ds_read_b128 v[168:171], v234 offset:19456
	v_mfma_f32_16x16x32_bf16 v[56:59], v[140:143], v[148:151], v[56:59]
	ds_read_b128 v[172:175], v234 offset:21504
	v_mfma_f32_16x16x32_bf16 v[52:55], v[144:147], v[148:151], v[52:55]
	ds_read_b128 v[176:179], v234 offset:23552
	v_mfma_f32_16x16x32_bf16 v[48:51], v[132:135], v[152:155], v[48:51]
	s_add_i32 m0, s40, 0x2000
	v_mfma_f32_16x16x32_bf16 v[44:47], v[136:139], v[152:155], v[44:47]
	global_load_lds_dwordx4 v188, s[28:29]
	v_mfma_f32_16x16x32_bf16 v[40:43], v[140:143], v[152:155], v[40:43]
	v_mfma_f32_16x16x32_bf16 v[36:39], v[144:147], v[152:155], v[36:39]
	s_add_u32 s98, s26, 0x80000
	s_addc_u32 s99, s27, 0
	s_add_i32 m0, s40, 0x14000
	v_mfma_f32_16x16x32_bf16 v[32:35], v[132:135], v[156:159], v[32:35]
	global_load_lds_dwordx4 v2, s[98:99]
	v_mfma_f32_16x16x32_bf16 v[28:31], v[136:139], v[156:159], v[28:31]
	v_mfma_f32_16x16x32_bf16 v[24:27], v[140:143], v[156:159], v[24:27]
	s_add_i32 m0, s40, 0x16000
	v_mfma_f32_16x16x32_bf16 v[20:23], v[144:147], v[156:159], v[20:23]
	global_load_lds_dwordx4 v0, s[98:99]
	v_mfma_f32_16x16x32_bf16 v[16:19], v[132:135], v[160:163], v[16:19]
	v_mfma_f32_16x16x32_bf16 v[12:15], v[136:139], v[160:163], v[12:15]
	v_mfma_f32_16x16x32_bf16 v[8:11], v[140:143], v[160:163], v[8:11]
	v_mfma_f32_16x16x32_bf16 v[4:7], v[144:147], v[160:163], v[4:7]
	s_waitcnt vmcnt(8) lgkmcnt(0)
	s_barrier
; #define PG8_STAGE(bufoff, gbase, voff) do { _Pragma("unroll") for (int _i = 0; _i < 2; ++_i) \
;         __builtin_amdgcn_global_load_lds((const unsigned*)((const char*)(gbase) + (voff)[_i]), (LAS unsigned*)(lds + (bufoff) + ldsw + _i * 8192), 16, 0, 0); } while (0)
; #define PG8_LDA(dst, b, h) do { _Pragma("unroll") for (int m = 0; m < 4; ++m) _Pragma("unroll") for (int k = 0; k < 2; ++k) dst[m][k] = *(const LAS bf16x8*)(lds + PG8_SA(b, h) + aoff + m * 2048 + k * 1024); } while (0)
; #define PG8_LDB(dst, b, h) do { _Pragma("unroll") for (int n = 0; n < 2; ++n) _Pragma("unroll") for (int k = 0; k < 2; ++k) dst[n][k] = *(const LAS bf16x8*)(lds + PG8_SB(b, h) + boff + n * 2048 + k * 1024); } while (0)
; #define PG8_MMA(ai, bj, At, Bt) do { __builtin_amdgcn_s_setprio(1); _Pragma("unroll") for (int m = 0; m < 4; ++m) _Pragma("unroll") for (int n = 0; n < 2; ++n) _Pragma("unroll") for (int k = 0; k < 2; ++k) \
;         acc[ai][bj][m][n] = __builtin_amdgcn_mfma_f32_16x16x32_bf16(Bt[n][k], At[m][k], acc[ai][bj][m][n], 0, 0, 0); __builtin_amdgcn_s_setprio(0); } while (0)
; #define PG8_WAIT_V(n) asm volatile("s_waitcnt vmcnt(" #n ")" ::: "memory")
; #define PG8_WAIT_L(n) asm volatile("s_waitcnt lgkmcnt(" #n ")" ::: "memory")
; #define PG8_BAR __builtin_amdgcn_s_barrier()
; #define PG8_SCHED __builtin_amdgcn_sched_barrier(0)
; template <class Epi, int LDA, int LDB, int KK>
; __device__ __forceinline__ void gemm_phase(int wv, LAS unsigned char* lds, const Gemm g, const StaticOrder& S, const Epi& E) {
;     ...
;             PG8_LDB(B0, 1, 0); PG8_SCHED; PG8_LDA(At, 1, 0); PG8_STAGE(PG8_SA(0, 1), a2 + hstepA, voffA);
;             PG8_WAIT_L(8); PG8_BAR; PG8_WAIT_L(0); PG8_MMA(0, 0, At, B0); PG8_BAR; PG8_SCHED;
;             PG8_LDB(B1, 1, 1); PG8_STAGE(PG8_SB(1, 0), b3, voffB);
;             PG8_BAR; PG8_WAIT_L(0); PG8_MMA(0, 1, At, B1); PG8_BAR;
;             PG8_LDA(At, 1, 1); PG8_STAGE(PG8_SA(1, 0), a3, voffA);
;             PG8_BAR; PG8_WAIT_L(0); PG8_MMA(1, 0, At, B0); PG8_BAR; PG8_SCHED;
;             PG8_STAGE(PG8_SB(1, 1), b3 + hstepB, voffB);
;             PG8_WAIT_V(6); PG8_BAR; PG8_MMA(1, 1, At, B1); PG8_BAR;
	v_mfma_f32_16x16x32_bf16 v[64:67], v[202:205], v[164:167], v[64:67]
	ds_read_b128 v[132:135], v180 offset:32768
	v_mfma_f32_16x16x32_bf16 v[60:63], v[206:209], v[164:167], v[60:63]
	ds_read_b128 v[136:139], v180 offset:34816
	v_mfma_f32_16x16x32_bf16 v[56:59], v[210:213], v[164:167], v[56:59]
	ds_read_b128 v[140:143], v180 offset:49152
	v_mfma_f32_16x16x32_bf16 v[52:55], v[214:217], v[164:167], v[52:55]
	ds_read_b128 v[144:147], v180 offset:51200
	v_mfma_f32_16x16x32_bf16 v[48:51], v[202:205], v[168:171], v[48:51]
	ds_read_b128 v[148:151], v234 offset:32768
	v_mfma_f32_16x16x32_bf16 v[44:47], v[206:209], v[168:171], v[44:47]
	ds_read_b128 v[152:155], v234 offset:34816
	v_mfma_f32_16x16x32_bf16 v[40:43], v[210:213], v[168:171], v[40:43]
	ds_read_b128 v[156:159], v234 offset:36864
	v_mfma_f32_16x16x32_bf16 v[36:39], v[214:217], v[168:171], v[36:39]
	ds_read_b128 v[160:163], v234 offset:38912
	v_mfma_f32_16x16x32_bf16 v[32:35], v[202:205], v[172:175], v[32:35]
	s_add_u32 s98, s28, 0x80000
	s_addc_u32 s99, s29, 0
	s_add_i32 m0, s40, 0x4000
	v_mfma_f32_16x16x32_bf16 v[28:31], v[206:209], v[172:175], v[28:31]
	global_load_lds_dwordx4 v190, s[98:99]
	v_mfma_f32_16x16x32_bf16 v[24:27], v[210:213], v[172:175], v[24:27]
	v_mfma_f32_16x16x32_bf16 v[20:23], v[214:217], v[172:175], v[20:23]
	s_add_i32 m0, s40, 0x6000
	v_mfma_f32_16x16x32_bf16 v[16:19], v[202:205], v[176:179], v[16:19]
	global_load_lds_dwordx4 v188, s[98:99]
	v_mfma_f32_16x16x32_bf16 v[12:15], v[206:209], v[176:179], v[12:15]
	v_mfma_f32_16x16x32_bf16 v[8:11], v[210:213], v[176:179], v[8:11]
	v_mfma_f32_16x16x32_bf16 v[4:7], v[214:217], v[176:179], v[4:7]
	s_waitcnt lgkmcnt(0)
	v_mfma_f32_16x16x32_bf16 v[128:131], v[132:135], v[148:151], v[128:131]
	ds_read_b128 v[202:205], v180 offset:33792
	v_mfma_f32_16x16x32_bf16 v[124:127], v[136:139], v[148:151], v[124:127]
	ds_read_b128 v[206:209], v180 offset:35840
	v_mfma_f32_16x16x32_bf16 v[120:123], v[140:143], v[148:151], v[120:123]
	ds_read_b128 v[210:213], v180 offset:50176
	v_mfma_f32_16x16x32_bf16 v[116:119], v[144:147], v[148:151], v[116:119]
	ds_read_b128 v[214:217], v180 offset:52224
	v_mfma_f32_16x16x32_bf16 v[112:115], v[132:135], v[152:155], v[112:115]
	ds_read_b128 v[164:167], v234 offset:33792
	v_mfma_f32_16x16x32_bf16 v[108:111], v[136:139], v[152:155], v[108:111]
	ds_read_b128 v[168:171], v234 offset:35840
	v_mfma_f32_16x16x32_bf16 v[104:107], v[140:143], v[152:155], v[104:107]
	ds_read_b128 v[172:175], v234 offset:37888
	v_mfma_f32_16x16x32_bf16 v[100:103], v[144:147], v[152:155], v[100:103]
	ds_read_b128 v[176:179], v234 offset:39936
	v_mfma_f32_16x16x32_bf16 v[96:99], v[132:135], v[156:159], v[96:99]
	v_mfma_f32_16x16x32_bf16 v[92:95], v[136:139], v[156:159], v[92:95]
	v_mfma_f32_16x16x32_bf16 v[88:91], v[140:143], v[156:159], v[88:91]
	v_mfma_f32_16x16x32_bf16 v[84:87], v[144:147], v[156:159], v[84:87]
	v_mfma_f32_16x16x32_bf16 v[80:83], v[132:135], v[160:163], v[80:83]
	v_mfma_f32_16x16x32_bf16 v[76:79], v[136:139], v[160:163], v[76:79]
	v_mfma_f32_16x16x32_bf16 v[72:75], v[140:143], v[160:163], v[72:75]
	v_mfma_f32_16x16x32_bf16 v[68:71], v[144:147], v[160:163], v[68:71]
	s_waitcnt vmcnt(8) lgkmcnt(0)
	s_barrier
	v_mfma_f32_16x16x32_bf16 v[128:131], v[202:205], v[164:167], v[128:131]
	ds_read_b128 v[148:151], v234 offset:49152
	v_mfma_f32_16x16x32_bf16 v[124:127], v[206:209], v[164:167], v[124:127]
	ds_read_b128 v[152:155], v234 offset:51200
	v_mfma_f32_16x16x32_bf16 v[120:123], v[210:213], v[164:167], v[120:123]
	ds_read_b128 v[156:159], v234 offset:53248
	v_mfma_f32_16x16x32_bf16 v[116:119], v[214:217], v[164:167], v[116:119]
	ds_read_b128 v[160:163], v234 offset:55296
	v_mfma_f32_16x16x32_bf16 v[112:115], v[202:205], v[168:171], v[112:115]
	s_add_i32 m0, s40, 0x17f80
	v_mfma_f32_16x16x32_bf16 v[108:111], v[206:209], v[168:171], v[108:111]
	global_load_lds_dwordx4 v2, s[26:27] offset:128
	v_mfma_f32_16x16x32_bf16 v[104:107], v[210:213], v[168:171], v[104:107]
	v_mfma_f32_16x16x32_bf16 v[100:103], v[214:217], v[168:171], v[100:103]
	s_add_i32 m0, s40, 0x19f80
	v_mfma_f32_16x16x32_bf16 v[96:99], v[202:205], v[172:175], v[96:99]
	global_load_lds_dwordx4 v0, s[26:27] offset:128
	v_mfma_f32_16x16x32_bf16 v[92:95], v[206:209], v[172:175], v[92:95]
	v_mfma_f32_16x16x32_bf16 v[88:91], v[210:213], v[172:175], v[88:91]
	s_add_i32 m0, s40, 0x7f80
	v_mfma_f32_16x16x32_bf16 v[84:87], v[214:217], v[172:175], v[84:87]
	global_load_lds_dwordx4 v190, s[28:29] offset:128
	v_mfma_f32_16x16x32_bf16 v[80:83], v[202:205], v[176:179], v[80:83]
	v_mfma_f32_16x16x32_bf16 v[76:79], v[206:209], v[176:179], v[76:79]
	v_mfma_f32_16x16x32_bf16 v[72:75], v[210:213], v[176:179], v[72:75]
	v_mfma_f32_16x16x32_bf16 v[68:71], v[214:217], v[176:179], v[68:71]
	s_waitcnt lgkmcnt(0)
	v_mfma_f32_16x16x32_bf16 v[64:67], v[132:135], v[148:151], v[64:67]
	ds_read_b128 v[164:167], v234 offset:50176
	v_mfma_f32_16x16x32_bf16 v[60:63], v[136:139], v[148:151], v[60:63]
	ds_read_b128 v[168:171], v234 offset:52224
	v_mfma_f32_16x16x32_bf16 v[56:59], v[140:143], v[148:151], v[56:59]
	ds_read_b128 v[172:175], v234 offset:54272
	v_mfma_f32_16x16x32_bf16 v[52:55], v[144:147], v[148:151], v[52:55]
	ds_read_b128 v[176:179], v234 offset:56320
	v_mfma_f32_16x16x32_bf16 v[48:51], v[132:135], v[152:155], v[48:51]
	s_add_i32 m0, s40, 0x9f80
	v_mfma_f32_16x16x32_bf16 v[44:47], v[136:139], v[152:155], v[44:47]
	global_load_lds_dwordx4 v188, s[28:29] offset:128
	v_mfma_f32_16x16x32_bf16 v[40:43], v[140:143], v[152:155], v[40:43]
	v_mfma_f32_16x16x32_bf16 v[36:39], v[144:147], v[152:155], v[36:39]
	s_add_u32 s98, s26, 0x80000
	s_addc_u32 s99, s27, 0
	s_add_i32 m0, s40, 0x1bf80
	v_mfma_f32_16x16x32_bf16 v[32:35], v[132:135], v[156:159], v[32:35]
	global_load_lds_dwordx4 v2, s[98:99] offset:128
	v_mfma_f32_16x16x32_bf16 v[28:31], v[136:139], v[156:159], v[28:31]
	v_mfma_f32_16x16x32_bf16 v[24:27], v[140:143], v[156:159], v[24:27]
	s_add_i32 m0, s40, 0x1df80
	v_mfma_f32_16x16x32_bf16 v[20:23], v[144:147], v[156:159], v[20:23]
	global_load_lds_dwordx4 v0, s[98:99] offset:128
	v_mfma_f32_16x16x32_bf16 v[16:19], v[132:135], v[160:163], v[16:19]
	v_mfma_f32_16x16x32_bf16 v[12:15], v[136:139], v[160:163], v[12:15]
	v_mfma_f32_16x16x32_bf16 v[8:11], v[140:143], v[160:163], v[8:11]
	v_mfma_f32_16x16x32_bf16 v[4:7], v[144:147], v[160:163], v[4:7]
	s_waitcnt vmcnt(8) lgkmcnt(0)
	s_barrier
; #define LAS __attribute__((address_space(3)))
; #define PG8_STAGE(bufoff, gbase, voff) do { _Pragma("unroll") for (int _i = 0; _i < 2; ++_i) \
;         __builtin_amdgcn_global_load_lds((const unsigned*)((const char*)(gbase) + (voff)[_i]), (LAS unsigned*)(lds + (bufoff) + ldsw + _i * 8192), 16, 0, 0); } while (0)
; #define PG8_LDA(dst, b, h) do { _Pragma("unroll") for (int m = 0; m < 4; ++m) _Pragma("unroll") for (int k = 0; k < 2; ++k) dst[m][k] = *(const LAS bf16x8*)(lds + PG8_SA(b, h) + aoff + m * 2048 + k * 1024); } while (0)
; #define PG8_MMA(ai, bj, At, Bt) do { __builtin_amdgcn_s_setprio(1); _Pragma("unroll") for (int m = 0; m < 4; ++m) _Pragma("unroll") for (int n = 0; n < 2; ++n) _Pragma("unroll") for (int k = 0; k < 2; ++k) \
;         acc[ai][bj][m][n] = __builtin_amdgcn_mfma_f32_16x16x32_bf16(Bt[n][k], At[m][k], acc[ai][bj][m][n], 0, 0, 0); __builtin_amdgcn_s_setprio(0); } while (0)
; #define PG8_WAIT_V(n) asm volatile("s_waitcnt vmcnt(" #n ")" ::: "memory")
; #define PG8_WAIT_L(n) asm volatile("s_waitcnt lgkmcnt(" #n ")" ::: "memory")
; #define PG8_BAR __builtin_amdgcn_s_barrier()
; #define PG8_SCHED __builtin_amdgcn_sched_barrier(0)
; template <class Epi, int LDA, int LDB, int KK>
; __device__ __forceinline__ void gemm_phase(int wv, LAS unsigned char* lds, const Gemm g, const StaticOrder& S, const Epi& E) {
;     ...
;             PG8_LDA(At, 1, 1); PG8_STAGE(PG8_SA(1, 0), a3, voffA);
;             PG8_BAR; PG8_WAIT_L(0); PG8_MMA(1, 0, At, B0); PG8_BAR; PG8_SCHED;
;             PG8_STAGE(PG8_SB(1, 1), b3 + hstepB, voffB);
;             PG8_WAIT_V(6); PG8_BAR; PG8_MMA(1, 1, At, B1); PG8_BAR;
;           }
;           if constexpr (Epi::HAS_MID) { if (seg < Epi::NSEG - 1) E.mid(acc, cur, seg, wr, wc, fr, fq); }
;         }
;         E(acc, cur, wr, wc, fr, fq, (const LAS float*)(lds + 131072 + (ui % 3) * 1024));
	v_mfma_f32_16x16x32_bf16 v[64:67], v[202:205], v[164:167], v[64:67]
	ds_read_b128 v[132:135], v180 offset:0
	v_mfma_f32_16x16x32_bf16 v[60:63], v[206:209], v[164:167], v[60:63]
	ds_read_b128 v[136:139], v180 offset:2048
	v_mfma_f32_16x16x32_bf16 v[56:59], v[210:213], v[164:167], v[56:59]
	ds_read_b128 v[140:143], v180 offset:16384
	v_mfma_f32_16x16x32_bf16 v[52:55], v[214:217], v[164:167], v[52:55]
	ds_read_b128 v[144:147], v180 offset:18432
	v_mfma_f32_16x16x32_bf16 v[48:51], v[202:205], v[168:171], v[48:51]
	ds_read_b128 v[148:151], v234 offset:0
	v_mfma_f32_16x16x32_bf16 v[44:47], v[206:209], v[168:171], v[44:47]
	ds_read_b128 v[152:155], v234 offset:2048
	v_mfma_f32_16x16x32_bf16 v[40:43], v[210:213], v[168:171], v[40:43]
	ds_read_b128 v[156:159], v234 offset:4096
	v_mfma_f32_16x16x32_bf16 v[36:39], v[214:217], v[168:171], v[36:39]
	ds_read_b128 v[160:163], v234 offset:6144
	v_mfma_f32_16x16x32_bf16 v[32:35], v[202:205], v[172:175], v[32:35]
	s_add_u32 s98, s28, 0x80000
	s_addc_u32 s99, s29, 0
	s_add_i32 m0, s40, 0xbf80
	v_mfma_f32_16x16x32_bf16 v[28:31], v[206:209], v[172:175], v[28:31]
	global_load_lds_dwordx4 v190, s[98:99] offset:128
	v_mfma_f32_16x16x32_bf16 v[24:27], v[210:213], v[172:175], v[24:27]
	v_mfma_f32_16x16x32_bf16 v[20:23], v[214:217], v[172:175], v[20:23]
	s_add_i32 m0, s40, 0xdf80
	v_mfma_f32_16x16x32_bf16 v[16:19], v[202:205], v[176:179], v[16:19]
	global_load_lds_dwordx4 v188, s[98:99] offset:128
	v_mfma_f32_16x16x32_bf16 v[12:15], v[206:209], v[176:179], v[12:15]
	v_mfma_f32_16x16x32_bf16 v[8:11], v[210:213], v[176:179], v[8:11]
	v_mfma_f32_16x16x32_bf16 v[4:7], v[214:217], v[176:179], v[4:7]
	s_add_i32 s69, s69, 2
	s_add_u32 s56, s56, 0x100
	s_addc_u32 s68, s68, 0
	s_add_u32 s24, s24, 0x100
	s_addc_u32 s25, s25, 0
	s_cmp_gt_u32 s69, 29
	s_cbranch_scc0 .Lout_loop
	s_waitcnt lgkmcnt(0)
	s_cmp_eq_u32 s100, 0
	s_cbranch_scc1 .Lot_epi
	s_cmp_eq_u32 s100, 4
	s_cbranch_scc1 .Lot_owner
	s_and_b32 s98, s81, 15
	s_mul_i32 s98, s98, 3
	s_add_u32 s98, s98, s100
	s_sub_u32 s98, s98, 1
	s_lshl_b32 s98, s98, 18
	s_add_u32 s98, s98, 0x1f000000
	s_add_u32 s98, s10, s98
	s_addc_u32 s99, s11, 0
	v_mbcnt_lo_u32_b32 v132, -1, 0
	v_mbcnt_hi_u32_b32 v132, -1, v132
	v_lshl_or_b32 v132, s95, 6, v132
	v_lshlrev_b32_e32 v132, 4, v132
	global_store_dwordx4 v132, v[4:7], s[98:99] sc0 sc1
	v_add_u32_e32 v132, 0x2000, v132
	global_store_dwordx4 v132, v[8:11], s[98:99] sc0 sc1
	v_add_u32_e32 v132, 0x2000, v132
	global_store_dwordx4 v132, v[12:15], s[98:99] sc0 sc1
	v_add_u32_e32 v132, 0x2000, v132
	global_store_dwordx4 v132, v[16:19], s[98:99] sc0 sc1
	v_add_u32_e32 v132, 0x2000, v132
	global_store_dwordx4 v132, v[20:23], s[98:99] sc0 sc1
	v_add_u32_e32 v132, 0x2000, v132
	global_store_dwordx4 v132, v[24:27], s[98:99] sc0 sc1
	v_add_u32_e32 v132, 0x2000, v132
	global_store_dwordx4 v132, v[28:31], s[98:99] sc0 sc1
	v_add_u32_e32 v132, 0x2000, v132
	global_store_dwordx4 v132, v[32:35], s[98:99] sc0 sc1
	v_add_u32_e32 v132, 0x2000, v132
	global_store_dwordx4 v132, v[36:39], s[98:99] sc0 sc1
	v_add_u32_e32 v132, 0x2000, v132
	global_store_dwordx4 v132, v[40:43], s[98:99] sc0 sc1
	v_add_u32_e32 v132, 0x2000, v132
	global_store_dwordx4 v132, v[44:47], s[98:99] sc0 sc1
	v_add_u32_e32 v132, 0x2000, v132
	global_store_dwordx4 v132, v[48:51], s[98:99] sc0 sc1
	v_add_u32_e32 v132, 0x2000, v132
	global_store_dwordx4 v132, v[52:55], s[98:99] sc0 sc1
	v_add_u32_e32 v132, 0x2000, v132
	global_store_dwordx4 v132, v[56:59], s[98:99] sc0 sc1
	v_add_u32_e32 v132, 0x2000, v132
	global_store_dwordx4 v132, v[60:63], s[98:99] sc0 sc1
	v_add_u32_e32 v132, 0x2000, v132
	global_store_dwordx4 v132, v[64:67], s[98:99] sc0 sc1
	v_add_u32_e32 v132, 0x2000, v132
	global_store_dwordx4 v132, v[68:71], s[98:99] sc0 sc1
	v_add_u32_e32 v132, 0x2000, v132
	global_store_dwordx4 v132, v[72:75], s[98:99] sc0 sc1
	v_add_u32_e32 v132, 0x2000, v132
	global_store_dwordx4 v132, v[76:79], s[98:99] sc0 sc1
	v_add_u32_e32 v132, 0x2000, v132
	global_store_dwordx4 v132, v[80:83], s[98:99] sc0 sc1
	v_add_u32_e32 v132, 0x2000, v132
	global_store_dwordx4 v132, v[84:87], s[98:99] sc0 sc1
	v_add_u32_e32 v132, 0x2000, v132
	global_store_dwordx4 v132, v[88:91], s[98:99] sc0 sc1
	v_add_u32_e32 v132, 0x2000, v132
	global_store_dwordx4 v132, v[92:95], s[98:99] sc0 sc1
	v_add_u32_e32 v132, 0x2000, v132
	global_store_dwordx4 v132, v[96:99], s[98:99] sc0 sc1
	v_add_u32_e32 v132, 0x2000, v132
	global_store_dwordx4 v132, v[100:103], s[98:99] sc0 sc1
	v_add_u32_e32 v132, 0x2000, v132
	global_store_dwordx4 v132, v[104:107], s[98:99] sc0 sc1
	v_add_u32_e32 v132, 0x2000, v132
	global_store_dwordx4 v132, v[108:111], s[98:99] sc0 sc1
	v_add_u32_e32 v132, 0x2000, v132
	global_store_dwordx4 v132, v[112:115], s[98:99] sc0 sc1
	v_add_u32_e32 v132, 0x2000, v132
	global_store_dwordx4 v132, v[116:119], s[98:99] sc0 sc1
	v_add_u32_e32 v132, 0x2000, v132
	global_store_dwordx4 v132, v[120:123], s[98:99] sc0 sc1
	v_add_u32_e32 v132, 0x2000, v132
	global_store_dwordx4 v132, v[124:127], s[98:99] sc0 sc1
	v_add_u32_e32 v132, 0x2000, v132
	global_store_dwordx4 v132, v[128:131], s[98:99] sc0 sc1
	s_waitcnt vmcnt(0)
	s_barrier
	s_cmp_lg_u32 s95, 0
	s_cbranch_scc1 .Lot_p_done
	s_and_b32 s98, s81, 15
	s_lshl_b32 s98, s98, 2
	s_add_u32 s98, s98, 0x285da940
	s_add_u32 s98, s10, s98
	s_addc_u32 s99, s11, 0
	s_mov_b64 exec, 1
	v_mov_b32_e32 v132, 0
	v_mov_b32_e32 v133, 1
	global_atomic_add v132, v133, s[98:99]
	s_mov_b64 exec, -1

; #define PG8_STAGE(bufoff, gbase, voff) do { _Pragma("unroll") for (int _i = 0; _i < 2; ++_i) \
;         __builtin_amdgcn_global_load_lds((const unsigned*)((const char*)(gbase) + (voff)[_i]), (LAS unsigned*)(lds + (bufoff) + ldsw + _i * 8192), 16, 0, 0); } while (0)
; #define PG8_LDA(dst, b, h) do { _Pragma("unroll") for (int m = 0; m < 4; ++m) _Pragma("unroll") for (int k = 0; k < 2; ++k) dst[m][k] = *(const LAS bf16x8*)(lds + PG8_SA(b, h) + aoff + m * 2048 + k * 1024); } while (0)
; #define PG8_LDB(dst, b, h) do { _Pragma("unroll") for (int n = 0; n < 2; ++n) _Pragma("unroll") for (int k = 0; k < 2; ++k) dst[n][k] = *(const LAS bf16x8*)(lds + PG8_SB(b, h) + boff + n * 2048 + k * 1024); } while (0)
; #define PG8_MMA(ai, bj, At, Bt) do { __builtin_amdgcn_s_setprio(1); _Pragma("unroll") for (int m = 0; m < 4; ++m) _Pragma("unroll") for (int n = 0; n < 2; ++n) _Pragma("unroll") for (int k = 0; k < 2; ++k) \
;         acc[ai][bj][m][n] = __builtin_amdgcn_mfma_f32_16x16x32_bf16(Bt[n][k], At[m][k], acc[ai][bj][m][n], 0, 0, 0); __builtin_amdgcn_s_setprio(0); } while (0)
; #define PG8_WAIT_V(n) asm volatile("s_waitcnt vmcnt(" #n ")" ::: "memory")
; #define PG8_WAIT_L(n) asm volatile("s_waitcnt lgkmcnt(" #n ")" ::: "memory")
; template <class Epi, int LDA, int LDB, int KK>
; __device__ __forceinline__ void gemm_phase(int wv, LAS unsigned char* lds, const Gemm g, const StaticOrder& S, const Epi& E) {
;     ...
;           for (; t < tend; t += 2) {
;             const bool last = (t == nt - 2);
;             const char* a1 = cA + (size_t)(t + 1) * kstep;
;             const char* a2 = last ? nA : cA + (size_t)(t + 2) * kstep; const char* b2 = last ? nB : cB + (size_t)(t + 2) * kstep;
;             const char* a3 = a2 + kstep; const char* b3 = b2 + kstep;
;             PG8_LDB(B0, 0, 0); PG8_SCHED; PG8_LDA(At, 0, 0); PG8_STAGE(PG8_SA(1, 1), a1 + hstepA, voffA);
;             PG8_WAIT_L(8); PG8_BAR; PG8_WAIT_L(0); PG8_MMA(0, 0, At, B0); PG8_BAR; PG8_SCHED;
;             PG8_LDB(B1, 0, 1); PG8_STAGE(PG8_SB(0, 0), b2, voffB);
;             PG8_BAR; PG8_WAIT_L(0); PG8_MMA(0, 1, At, B1); PG8_BAR;
;             PG8_LDA(At, 0, 1); PG8_STAGE(PG8_SA(0, 0), a2, voffA);
;             PG8_BAR; PG8_WAIT_L(0); PG8_MMA(1, 0, At, B0); PG8_BAR; PG8_SCHED;
;             PG8_STAGE(PG8_SB(0, 1), b2 + hstepB, voffB);
;             PG8_WAIT_V(6); PG8_BAR; PG8_MMA(1, 1, At, B1); PG8_BAR;
.Lup_loop:
	s_add_u32 s26, s6, 0xfff80080
	s_addc_u32 s27, s7, -1
	s_cmp_eq_u32 s56, 28
	s_cselect_b32 s29, s17, s27
	s_cselect_b32 s28, s45, s26
	s_cselect_b32 s27, s15, s55
	s_cselect_b32 s26, s46, s47
	s_waitcnt lgkmcnt(0)
	v_mfma_f32_16x16x32_bf16 v[128:131], v[148:151], v[164:167], v[128:131]
	ds_read_b128 v[202:205], v147 offset:1024
	v_mfma_f32_16x16x32_bf16 v[124:127], v[152:155], v[164:167], v[124:127]
	ds_read_b128 v[206:209], v147 offset:3072
	v_mfma_f32_16x16x32_bf16 v[120:123], v[156:159], v[164:167], v[120:123]
	ds_read_b128 v[210:213], v147 offset:17408
	v_mfma_f32_16x16x32_bf16 v[116:119], v[160:163], v[164:167], v[116:119]
	ds_read_b128 v[214:217], v147 offset:19456
	v_mfma_f32_16x16x32_bf16 v[112:115], v[148:151], v[168:171], v[112:115]
	ds_read_b128 v[180:183], v146 offset:1024
	v_mfma_f32_16x16x32_bf16 v[108:111], v[152:155], v[168:171], v[108:111]
	ds_read_b128 v[184:187], v146 offset:3072
	v_mfma_f32_16x16x32_bf16 v[104:107], v[156:159], v[168:171], v[104:107]
	ds_read_b128 v[188:191], v146 offset:5120
	v_mfma_f32_16x16x32_bf16 v[100:103], v[160:163], v[168:171], v[100:103]
	ds_read_b128 v[192:195], v146 offset:7168
	v_mfma_f32_16x16x32_bf16 v[96:99], v[148:151], v[172:175], v[96:99]
	v_mfma_f32_16x16x32_bf16 v[92:95], v[152:155], v[172:175], v[92:95]
	v_mfma_f32_16x16x32_bf16 v[88:91], v[156:159], v[172:175], v[88:91]
	v_mfma_f32_16x16x32_bf16 v[84:87], v[160:163], v[172:175], v[84:87]
	v_mfma_f32_16x16x32_bf16 v[80:83], v[148:151], v[176:179], v[80:83]
	v_mfma_f32_16x16x32_bf16 v[76:79], v[152:155], v[176:179], v[76:79]
	v_mfma_f32_16x16x32_bf16 v[72:75], v[156:159], v[176:179], v[72:75]
	v_mfma_f32_16x16x32_bf16 v[68:71], v[160:163], v[176:179], v[68:71]
	s_waitcnt vmcnt(8) lgkmcnt(0)
	s_barrier
	v_mfma_f32_16x16x32_bf16 v[128:131], v[202:205], v[180:183], v[128:131]
	ds_read_b128 v[164:167], v146 offset:16384
	v_mfma_f32_16x16x32_bf16 v[124:127], v[206:209], v[180:183], v[124:127]
	ds_read_b128 v[168:171], v146 offset:18432
	v_mfma_f32_16x16x32_bf16 v[120:123], v[210:213], v[180:183], v[120:123]
	ds_read_b128 v[172:175], v146 offset:20480
	v_mfma_f32_16x16x32_bf16 v[116:119], v[214:217], v[180:183], v[116:119]
	ds_read_b128 v[176:179], v146 offset:22528
	v_mfma_f32_16x16x32_bf16 v[112:115], v[202:205], v[184:187], v[112:115]
	s_add_i32 m0, s25, 0x10000
	v_mfma_f32_16x16x32_bf16 v[108:111], v[206:209], v[184:187], v[108:111]
	global_load_lds_dwordx4 v2, s[26:27]
	v_mfma_f32_16x16x32_bf16 v[104:107], v[210:213], v[184:187], v[104:107]
	v_mfma_f32_16x16x32_bf16 v[100:103], v[214:217], v[184:187], v[100:103]
	s_add_i32 m0, s25, 0x12000
	v_mfma_f32_16x16x32_bf16 v[96:99], v[202:205], v[188:191], v[96:99]
	global_load_lds_dwordx4 v134, s[26:27]
	v_mfma_f32_16x16x32_bf16 v[92:95], v[206:209], v[188:191], v[92:95]
	v_mfma_f32_16x16x32_bf16 v[88:91], v[210:213], v[188:191], v[88:91]
	s_mov_b32 m0, s25
	v_mfma_f32_16x16x32_bf16 v[84:87], v[214:217], v[188:191], v[84:87]
	global_load_lds_dwordx4 v0, s[28:29]
	v_mfma_f32_16x16x32_bf16 v[80:83], v[202:205], v[192:195], v[80:83]
	v_mfma_f32_16x16x32_bf16 v[76:79], v[206:209], v[192:195], v[76:79]
	v_mfma_f32_16x16x32_bf16 v[72:75], v[210:213], v[192:195], v[72:75]
	v_mfma_f32_16x16x32_bf16 v[68:71], v[214:217], v[192:195], v[68:71]
	s_waitcnt lgkmcnt(0)
	v_mfma_f32_16x16x32_bf16 v[64:67], v[148:151], v[164:167], v[64:67]
	ds_read_b128 v[180:183], v146 offset:17408
	v_mfma_f32_16x16x32_bf16 v[60:63], v[152:155], v[164:167], v[60:63]
	ds_read_b128 v[184:187], v146 offset:19456
	v_mfma_f32_16x16x32_bf16 v[56:59], v[156:159], v[164:167], v[56:59]
	ds_read_b128 v[188:191], v146 offset:21504
	v_mfma_f32_16x16x32_bf16 v[52:55], v[160:163], v[164:167], v[52:55]
	ds_read_b128 v[192:195], v146 offset:23552
	v_mfma_f32_16x16x32_bf16 v[48:51], v[148:151], v[168:171], v[48:51]
	s_add_i32 m0, s25, 0x2000
	v_mfma_f32_16x16x32_bf16 v[44:47], v[152:155], v[168:171], v[44:47]
	global_load_lds_dwordx4 v132, s[28:29]
	v_mfma_f32_16x16x32_bf16 v[40:43], v[156:159], v[168:171], v[40:43]
	v_mfma_f32_16x16x32_bf16 v[36:39], v[160:163], v[168:171], v[36:39]
	s_add_u32 s98, s26, 0x80000
	s_addc_u32 s99, s27, 0
	s_add_i32 m0, s25, 0x14000
	v_mfma_f32_16x16x32_bf16 v[32:35], v[148:151], v[172:175], v[32:35]
	global_load_lds_dwordx4 v2, s[98:99]
	v_mfma_f32_16x16x32_bf16 v[28:31], v[152:155], v[172:175], v[28:31]
	v_mfma_f32_16x16x32_bf16 v[24:27], v[156:159], v[172:175], v[24:27]
	s_add_i32 m0, s25, 0x16000
	v_mfma_f32_16x16x32_bf16 v[20:23], v[160:163], v[172:175], v[20:23]
	global_load_lds_dwordx4 v134, s[98:99]
	v_mfma_f32_16x16x32_bf16 v[16:19], v[148:151], v[176:179], v[16:19]
	v_mfma_f32_16x16x32_bf16 v[12:15], v[152:155], v[176:179], v[12:15]
	v_mfma_f32_16x16x32_bf16 v[8:11], v[156:159], v[176:179], v[8:11]
	v_mfma_f32_16x16x32_bf16 v[4:7], v[160:163], v[176:179], v[4:7]
	s_waitcnt vmcnt(8) lgkmcnt(0)
	s_barrier
; #define PG8_STAGE(bufoff, gbase, voff) do { _Pragma("unroll") for (int _i = 0; _i < 2; ++_i) \
;         __builtin_amdgcn_global_load_lds((const unsigned*)((const char*)(gbase) + (voff)[_i]), (LAS unsigned*)(lds + (bufoff) + ldsw + _i * 8192), 16, 0, 0); } while (0)
; #define PG8_LDA(dst, b, h) do { _Pragma("unroll") for (int m = 0; m < 4; ++m) _Pragma("unroll") for (int k = 0; k < 2; ++k) dst[m][k] = *(const LAS bf16x8*)(lds + PG8_SA(b, h) + aoff + m * 2048 + k * 1024); } while (0)
; #define PG8_LDB(dst, b, h) do { _Pragma("unroll") for (int n = 0; n < 2; ++n) _Pragma("unroll") for (int k = 0; k < 2; ++k) dst[n][k] = *(const LAS bf16x8*)(lds + PG8_SB(b, h) + boff + n * 2048 + k * 1024); } while (0)
; #define PG8_MMA(ai, bj, At, Bt) do { __builtin_amdgcn_s_setprio(1); _Pragma("unroll") for (int m = 0; m < 4; ++m) _Pragma("unroll") for (int n = 0; n < 2; ++n) _Pragma("unroll") for (int k = 0; k < 2; ++k) \
;         acc[ai][bj][m][n] = __builtin_amdgcn_mfma_f32_16x16x32_bf16(Bt[n][k], At[m][k], acc[ai][bj][m][n], 0, 0, 0); __builtin_amdgcn_s_setprio(0); } while (0)
; #define PG8_WAIT_V(n) asm volatile("s_waitcnt vmcnt(" #n ")" ::: "memory")
; #define PG8_WAIT_L(n) asm volatile("s_waitcnt lgkmcnt(" #n ")" ::: "memory")
; #define PG8_BAR __builtin_amdgcn_s_barrier()
; #define PG8_SCHED __builtin_amdgcn_sched_barrier(0)
; template <class Epi, int LDA, int LDB, int KK>
; __device__ __forceinline__ void gemm_phase(int wv, LAS unsigned char* lds, const Gemm g, const StaticOrder& S, const Epi& E) {
;     ...
;             PG8_LDB(B0, 1, 0); PG8_SCHED; PG8_LDA(At, 1, 0); PG8_STAGE(PG8_SA(0, 1), a2 + hstepA, voffA);
;             PG8_WAIT_L(8); PG8_BAR; PG8_WAIT_L(0); PG8_MMA(0, 0, At, B0); PG8_BAR; PG8_SCHED;
;             PG8_LDB(B1, 1, 1); PG8_STAGE(PG8_SB(1, 0), b3, voffB);
;             PG8_BAR; PG8_WAIT_L(0); PG8_MMA(0, 1, At, B1); PG8_BAR;
;             PG8_LDA(At, 1, 1); PG8_STAGE(PG8_SA(1, 0), a3, voffA);
;             PG8_BAR; PG8_WAIT_L(0); PG8_MMA(1, 0, At, B0); PG8_BAR; PG8_SCHED;
;             PG8_STAGE(PG8_SB(1, 1), b3 + hstepB, voffB);
;             PG8_WAIT_V(6); PG8_BAR; PG8_MMA(1, 1, At, B1); PG8_BAR;
	v_mfma_f32_16x16x32_bf16 v[64:67], v[202:205], v[180:183], v[64:67]
	ds_read_b128 v[148:151], v147 offset:32768
	v_mfma_f32_16x16x32_bf16 v[60:63], v[206:209], v[180:183], v[60:63]
	ds_read_b128 v[152:155], v147 offset:34816
	v_mfma_f32_16x16x32_bf16 v[56:59], v[210:213], v[180:183], v[56:59]
	ds_read_b128 v[156:159], v147 offset:49152
	v_mfma_f32_16x16x32_bf16 v[52:55], v[214:217], v[180:183], v[52:55]
	ds_read_b128 v[160:163], v147 offset:51200
	v_mfma_f32_16x16x32_bf16 v[48:51], v[202:205], v[184:187], v[48:51]
	ds_read_b128 v[164:167], v146 offset:32768
	v_mfma_f32_16x16x32_bf16 v[44:47], v[206:209], v[184:187], v[44:47]
	ds_read_b128 v[168:171], v146 offset:34816
	v_mfma_f32_16x16x32_bf16 v[40:43], v[210:213], v[184:187], v[40:43]
	ds_read_b128 v[172:175], v146 offset:36864
	v_mfma_f32_16x16x32_bf16 v[36:39], v[214:217], v[184:187], v[36:39]
	ds_read_b128 v[176:179], v146 offset:38912
	v_mfma_f32_16x16x32_bf16 v[32:35], v[202:205], v[188:191], v[32:35]
	s_add_u32 s98, s28, 0x80000
	s_addc_u32 s99, s29, 0
	s_add_i32 m0, s25, 0x4000
	v_mfma_f32_16x16x32_bf16 v[28:31], v[206:209], v[188:191], v[28:31]
	global_load_lds_dwordx4 v0, s[98:99]
	v_mfma_f32_16x16x32_bf16 v[24:27], v[210:213], v[188:191], v[24:27]
	v_mfma_f32_16x16x32_bf16 v[20:23], v[214:217], v[188:191], v[20:23]
	s_add_i32 m0, s25, 0x6000
	v_mfma_f32_16x16x32_bf16 v[16:19], v[202:205], v[192:195], v[16:19]
	global_load_lds_dwordx4 v132, s[98:99]
	v_mfma_f32_16x16x32_bf16 v[12:15], v[206:209], v[192:195], v[12:15]
	v_mfma_f32_16x16x32_bf16 v[8:11], v[210:213], v[192:195], v[8:11]
	v_mfma_f32_16x16x32_bf16 v[4:7], v[214:217], v[192:195], v[4:7]
	s_waitcnt lgkmcnt(0)
	v_mfma_f32_16x16x32_bf16 v[128:131], v[148:151], v[164:167], v[128:131]
	ds_read_b128 v[202:205], v147 offset:33792
	v_mfma_f32_16x16x32_bf16 v[124:127], v[152:155], v[164:167], v[124:127]
	ds_read_b128 v[206:209], v147 offset:35840
	v_mfma_f32_16x16x32_bf16 v[120:123], v[156:159], v[164:167], v[120:123]
	ds_read_b128 v[210:213], v147 offset:50176
	v_mfma_f32_16x16x32_bf16 v[116:119], v[160:163], v[164:167], v[116:119]
	ds_read_b128 v[214:217], v147 offset:52224
	v_mfma_f32_16x16x32_bf16 v[112:115], v[148:151], v[168:171], v[112:115]
	ds_read_b128 v[180:183], v146 offset:33792
	v_mfma_f32_16x16x32_bf16 v[108:111], v[152:155], v[168:171], v[108:111]
	ds_read_b128 v[184:187], v146 offset:35840
	v_mfma_f32_16x16x32_bf16 v[104:107], v[156:159], v[168:171], v[104:107]
	ds_read_b128 v[188:191], v146 offset:37888
	v_mfma_f32_16x16x32_bf16 v[100:103], v[160:163], v[168:171], v[100:103]
	ds_read_b128 v[192:195], v146 offset:39936
	v_mfma_f32_16x16x32_bf16 v[96:99], v[148:151], v[172:175], v[96:99]
	v_mfma_f32_16x16x32_bf16 v[92:95], v[152:155], v[172:175], v[92:95]
	v_mfma_f32_16x16x32_bf16 v[88:91], v[156:159], v[172:175], v[88:91]
	v_mfma_f32_16x16x32_bf16 v[84:87], v[160:163], v[172:175], v[84:87]
	v_mfma_f32_16x16x32_bf16 v[80:83], v[148:151], v[176:179], v[80:83]
	v_mfma_f32_16x16x32_bf16 v[76:79], v[152:155], v[176:179], v[76:79]
	v_mfma_f32_16x16x32_bf16 v[72:75], v[156:159], v[176:179], v[72:75]
	v_mfma_f32_16x16x32_bf16 v[68:71], v[160:163], v[176:179], v[68:71]
	s_waitcnt vmcnt(8) lgkmcnt(0)
	s_barrier
	v_mfma_f32_16x16x32_bf16 v[128:131], v[202:205], v[180:183], v[128:131]
	ds_read_b128 v[164:167], v146 offset:49152
	v_mfma_f32_16x16x32_bf16 v[124:127], v[206:209], v[180:183], v[124:127]
	ds_read_b128 v[168:171], v146 offset:51200
	v_mfma_f32_16x16x32_bf16 v[120:123], v[210:213], v[180:183], v[120:123]
	ds_read_b128 v[172:175], v146 offset:53248
	v_mfma_f32_16x16x32_bf16 v[116:119], v[214:217], v[180:183], v[116:119]
	ds_read_b128 v[176:179], v146 offset:55296
	v_mfma_f32_16x16x32_bf16 v[112:115], v[202:205], v[184:187], v[112:115]
	s_add_i32 m0, s25, 0x17f80
	v_mfma_f32_16x16x32_bf16 v[108:111], v[206:209], v[184:187], v[108:111]
	global_load_lds_dwordx4 v2, s[26:27] offset:128
	v_mfma_f32_16x16x32_bf16 v[104:107], v[210:213], v[184:187], v[104:107]
	v_mfma_f32_16x16x32_bf16 v[100:103], v[214:217], v[184:187], v[100:103]
	s_add_i32 m0, s25, 0x19f80
	v_mfma_f32_16x16x32_bf16 v[96:99], v[202:205], v[188:191], v[96:99]
	global_load_lds_dwordx4 v134, s[26:27] offset:128
	v_mfma_f32_16x16x32_bf16 v[92:95], v[206:209], v[188:191], v[92:95]
	v_mfma_f32_16x16x32_bf16 v[88:91], v[210:213], v[188:191], v[88:91]
	s_add_i32 m0, s25, 0x7f80
	v_mfma_f32_16x16x32_bf16 v[84:87], v[214:217], v[188:191], v[84:87]
	global_load_lds_dwordx4 v0, s[28:29] offset:128
	v_mfma_f32_16x16x32_bf16 v[80:83], v[202:205], v[192:195], v[80:83]
	v_mfma_f32_16x16x32_bf16 v[76:79], v[206:209], v[192:195], v[76:79]
	v_mfma_f32_16x16x32_bf16 v[72:75], v[210:213], v[192:195], v[72:75]
	v_mfma_f32_16x16x32_bf16 v[68:71], v[214:217], v[192:195], v[68:71]
	s_waitcnt lgkmcnt(0)
	v_mfma_f32_16x16x32_bf16 v[64:67], v[148:151], v[164:167], v[64:67]
	ds_read_b128 v[180:183], v146 offset:50176
	v_mfma_f32_16x16x32_bf16 v[60:63], v[152:155], v[164:167], v[60:63]
	ds_read_b128 v[184:187], v146 offset:52224
	v_mfma_f32_16x16x32_bf16 v[56:59], v[156:159], v[164:167], v[56:59]
	ds_read_b128 v[188:191], v146 offset:54272
	v_mfma_f32_16x16x32_bf16 v[52:55], v[160:163], v[164:167], v[52:55]
	ds_read_b128 v[192:195], v146 offset:56320
	v_mfma_f32_16x16x32_bf16 v[48:51], v[148:151], v[168:171], v[48:51]
	s_add_i32 m0, s25, 0x9f80
	v_mfma_f32_16x16x32_bf16 v[44:47], v[152:155], v[168:171], v[44:47]
	global_load_lds_dwordx4 v132, s[28:29] offset:128
	v_mfma_f32_16x16x32_bf16 v[40:43], v[156:159], v[168:171], v[40:43]
	v_mfma_f32_16x16x32_bf16 v[36:39], v[160:163], v[168:171], v[36:39]
	s_add_u32 s98, s26, 0x80000
	s_addc_u32 s99, s27, 0
	s_add_i32 m0, s25, 0x1bf80
	v_mfma_f32_16x16x32_bf16 v[32:35], v[148:151], v[172:175], v[32:35]
	global_load_lds_dwordx4 v2, s[98:99] offset:128
	v_mfma_f32_16x16x32_bf16 v[28:31], v[152:155], v[172:175], v[28:31]
	v_mfma_f32_16x16x32_bf16 v[24:27], v[156:159], v[172:175], v[24:27]
	s_add_i32 m0, s25, 0x1df80
	v_mfma_f32_16x16x32_bf16 v[20:23], v[160:163], v[172:175], v[20:23]
	global_load_lds_dwordx4 v134, s[98:99] offset:128
	v_mfma_f32_16x16x32_bf16 v[16:19], v[148:151], v[176:179], v[16:19]
	v_mfma_f32_16x16x32_bf16 v[12:15], v[152:155], v[176:179], v[12:15]
	v_mfma_f32_16x16x32_bf16 v[8:11], v[156:159], v[176:179], v[8:11]
	v_mfma_f32_16x16x32_bf16 v[4:7], v[160:163], v[176:179], v[4:7]
	s_waitcnt vmcnt(8) lgkmcnt(0)
	s_barrier
; #define LAS __attribute__((address_space(3)))
; #define PG8_STAGE(bufoff, gbase, voff) do { _Pragma("unroll") for (int _i = 0; _i < 2; ++_i) \
;         __builtin_amdgcn_global_load_lds((const unsigned*)((const char*)(gbase) + (voff)[_i]), (LAS unsigned*)(lds + (bufoff) + ldsw + _i * 8192), 16, 0, 0); } while (0)
; #define PG8_LDA(dst, b, h) do { _Pragma("unroll") for (int m = 0; m < 4; ++m) _Pragma("unroll") for (int k = 0; k < 2; ++k) dst[m][k] = *(const LAS bf16x8*)(lds + PG8_SA(b, h) + aoff + m * 2048 + k * 1024); } while (0)
; #define PG8_MMA(ai, bj, At, Bt) do { __builtin_amdgcn_s_setprio(1); _Pragma("unroll") for (int m = 0; m < 4; ++m) _Pragma("unroll") for (int n = 0; n < 2; ++n) _Pragma("unroll") for (int k = 0; k < 2; ++k) \
;         acc[ai][bj][m][n] = __builtin_amdgcn_mfma_f32_16x16x32_bf16(Bt[n][k], At[m][k], acc[ai][bj][m][n], 0, 0, 0); __builtin_amdgcn_s_setprio(0); } while (0)
; #define PG8_WAIT_V(n) asm volatile("s_waitcnt vmcnt(" #n ")" ::: "memory")
; #define PG8_WAIT_L(n) asm volatile("s_waitcnt lgkmcnt(" #n ")" ::: "memory")
; #define PG8_BAR __builtin_amdgcn_s_barrier()
; #define PG8_SCHED __builtin_amdgcn_sched_barrier(0)
; template <class Epi, int LDA, int LDB, int KK>
; __device__ __forceinline__ void gemm_phase(int wv, LAS unsigned char* lds, const Gemm g, const StaticOrder& S, const Epi& E) {
;     ...
;             PG8_LDA(At, 1, 1); PG8_STAGE(PG8_SA(1, 0), a3, voffA);
;             PG8_BAR; PG8_WAIT_L(0); PG8_MMA(1, 0, At, B0); PG8_BAR; PG8_SCHED;
;             PG8_STAGE(PG8_SB(1, 1), b3 + hstepB, voffB);
;             PG8_WAIT_V(6); PG8_BAR; PG8_MMA(1, 1, At, B1); PG8_BAR;
;           }
;           if constexpr (Epi::HAS_MID) { if (seg < Epi::NSEG - 1) E.mid(acc, cur, seg, wr, wc, fr, fq); }
;         }
;         E(acc, cur, wr, wc, fr, fq, (const LAS float*)(lds + 131072 + (ui % 3) * 1024));
	v_mfma_f32_16x16x32_bf16 v[64:67], v[202:205], v[180:183], v[64:67]
	ds_read_b128 v[148:151], v147 offset:0
	v_mfma_f32_16x16x32_bf16 v[60:63], v[206:209], v[180:183], v[60:63]
	ds_read_b128 v[152:155], v147 offset:2048
	v_mfma_f32_16x16x32_bf16 v[56:59], v[210:213], v[180:183], v[56:59]
	ds_read_b128 v[156:159], v147 offset:16384
	v_mfma_f32_16x16x32_bf16 v[52:55], v[214:217], v[180:183], v[52:55]
	ds_read_b128 v[160:163], v147 offset:18432
	v_mfma_f32_16x16x32_bf16 v[48:51], v[202:205], v[184:187], v[48:51]
	ds_read_b128 v[164:167], v146 offset:0
	v_mfma_f32_16x16x32_bf16 v[44:47], v[206:209], v[184:187], v[44:47]
	ds_read_b128 v[168:171], v146 offset:2048
	v_mfma_f32_16x16x32_bf16 v[40:43], v[210:213], v[184:187], v[40:43]
	ds_read_b128 v[172:175], v146 offset:4096
	v_mfma_f32_16x16x32_bf16 v[36:39], v[214:217], v[184:187], v[36:39]
	ds_read_b128 v[176:179], v146 offset:6144
	v_mfma_f32_16x16x32_bf16 v[32:35], v[202:205], v[188:191], v[32:35]
	s_add_u32 s98, s28, 0x80000
	s_addc_u32 s99, s29, 0
	s_add_i32 m0, s25, 0xbf80
	v_mfma_f32_16x16x32_bf16 v[28:31], v[206:209], v[188:191], v[28:31]
	global_load_lds_dwordx4 v0, s[98:99] offset:128
	v_mfma_f32_16x16x32_bf16 v[24:27], v[210:213], v[188:191], v[24:27]
	v_mfma_f32_16x16x32_bf16 v[20:23], v[214:217], v[188:191], v[20:23]
	s_add_i32 m0, s25, 0xdf80
	v_mfma_f32_16x16x32_bf16 v[16:19], v[202:205], v[192:195], v[16:19]
	global_load_lds_dwordx4 v132, s[98:99] offset:128
	v_mfma_f32_16x16x32_bf16 v[12:15], v[206:209], v[192:195], v[12:15]
	v_mfma_f32_16x16x32_bf16 v[8:11], v[210:213], v[192:195], v[8:11]
	v_mfma_f32_16x16x32_bf16 v[4:7], v[214:217], v[192:195], v[4:7]
	s_add_i32 s56, s56, 2
	s_add_u32 s47, s47, 0x100
	s_addc_u32 s55, s55, 0
	s_add_u32 s6, s6, 0x100
	s_addc_u32 s7, s7, 0
	s_cmp_gt_u32 s56, 29
	s_cbranch_scc0 .Lup_loop
	s_waitcnt lgkmcnt(0)
	s_cmp_eq_u32 s100, 0
	s_cbranch_scc1 .Lut_epi
	s_cmp_eq_u32 s100, 2
	s_cbranch_scc1 .Lut_owner
	s_sub_u32 s98, s81, 88
	s_cmp_lt_u32 s81, 88
	s_cselect_b32 s98, s81, s98
	s_lshl_b32 s98, s98, 18
	s_add_u32 s98, s98, 0x16c00000
	s_add_u32 s98, s10, s98
	s_addc_u32 s99, s11, 0
	v_mbcnt_lo_u32_b32 v148, -1, 0
	v_mbcnt_hi_u32_b32 v148, -1, v148
	v_lshl_or_b32 v148, s95, 6, v148
	v_lshlrev_b32_e32 v148, 4, v148
	global_store_dwordx4 v148, v[4:7], s[98:99] sc0 sc1
	v_add_u32_e32 v148, 0x2000, v148
	global_store_dwordx4 v148, v[8:11], s[98:99] sc0 sc1
	v_add_u32_e32 v148, 0x2000, v148
	global_store_dwordx4 v148, v[12:15], s[98:99] sc0 sc1
	v_add_u32_e32 v148, 0x2000, v148
	global_store_dwordx4 v148, v[16:19], s[98:99] sc0 sc1
	v_add_u32_e32 v148, 0x2000, v148
	global_store_dwordx4 v148, v[20:23], s[98:99] sc0 sc1
	v_add_u32_e32 v148, 0x2000, v148
	global_store_dwordx4 v148, v[24:27], s[98:99] sc0 sc1
	v_add_u32_e32 v148, 0x2000, v148
	global_store_dwordx4 v148, v[28:31], s[98:99] sc0 sc1
	v_add_u32_e32 v148, 0x2000, v148
	global_store_dwordx4 v148, v[32:35], s[98:99] sc0 sc1
	v_add_u32_e32 v148, 0x2000, v148
	global_store_dwordx4 v148, v[36:39], s[98:99] sc0 sc1
	v_add_u32_e32 v148, 0x2000, v148
	global_store_dwordx4 v148, v[40:43], s[98:99] sc0 sc1
	v_add_u32_e32 v148, 0x2000, v148
	global_store_dwordx4 v148, v[44:47], s[98:99] sc0 sc1
	v_add_u32_e32 v148, 0x2000, v148
	global_store_dwordx4 v148, v[48:51], s[98:99] sc0 sc1
	v_add_u32_e32 v148, 0x2000, v148
	global_store_dwordx4 v148, v[52:55], s[98:99] sc0 sc1
	v_add_u32_e32 v148, 0x2000, v148
	global_store_dwordx4 v148, v[56:59], s[98:99] sc0 sc1
	v_add_u32_e32 v148, 0x2000, v148
	global_store_dwordx4 v148, v[60:63], s[98:99] sc0 sc1
	v_add_u32_e32 v148, 0x2000, v148
	global_store_dwordx4 v148, v[64:67], s[98:99] sc0 sc1
	v_add_u32_e32 v148, 0x2000, v148
	global_store_dwordx4 v148, v[68:71], s[98:99] sc0 sc1
	v_add_u32_e32 v148, 0x2000, v148
	global_store_dwordx4 v148, v[72:75], s[98:99] sc0 sc1
	v_add_u32_e32 v148, 0x2000, v148
	global_store_dwordx4 v148, v[76:79], s[98:99] sc0 sc1
	v_add_u32_e32 v148, 0x2000, v148
	global_store_dwordx4 v148, v[80:83], s[98:99] sc0 sc1
	v_add_u32_e32 v148, 0x2000, v148
	global_store_dwordx4 v148, v[84:87], s[98:99] sc0 sc1
	v_add_u32_e32 v148, 0x2000, v148
	global_store_dwordx4 v148, v[88:91], s[98:99] sc0 sc1
	v_add_u32_e32 v148, 0x2000, v148
	global_store_dwordx4 v148, v[92:95], s[98:99] sc0 sc1
	v_add_u32_e32 v148, 0x2000, v148
	global_store_dwordx4 v148, v[96:99], s[98:99] sc0 sc1
	v_add_u32_e32 v148, 0x2000, v148
	global_store_dwordx4 v148, v[100:103], s[98:99] sc0 sc1
	v_add_u32_e32 v148, 0x2000, v148
	global_store_dwordx4 v148, v[104:107], s[98:99] sc0 sc1
	v_add_u32_e32 v148, 0x2000, v148
	global_store_dwordx4 v148, v[108:111], s[98:99] sc0 sc1
	v_add_u32_e32 v148, 0x2000, v148
	global_store_dwordx4 v148, v[112:115], s[98:99] sc0 sc1
	v_add_u32_e32 v148, 0x2000, v148
	global_store_dwordx4 v148, v[116:119], s[98:99] sc0 sc1
	v_add_u32_e32 v148, 0x2000, v148
	global_store_dwordx4 v148, v[120:123], s[98:99] sc0 sc1
	v_add_u32_e32 v148, 0x2000, v148
	global_store_dwordx4 v148, v[124:127], s[98:99] sc0 sc1
	v_add_u32_e32 v148, 0x2000, v148
	global_store_dwordx4 v148, v[128:131], s[98:99] sc0 sc1
	s_waitcnt vmcnt(0)
	s_barrier
	s_cmp_lg_u32 s95, 0
	s_cbranch_scc1 .Lut_p_done
	s_sub_u32 s98, s81, 88
	s_cmp_lt_u32 s81, 88
	s_cselect_b32 s98, s81, s98
	s_add_u32 s99, s98, 32
	s_cmp_lt_u32 s98, 64
	s_cselect_b32 s98, s98, s99
	s_lshl_b32 s98, s98, 2
	s_add_u32 s98, s98, 0x201da800
	s_add_u32 s98, s10, s98
	s_addc_u32 s99, s11, 0
	s_mov_b64 exec, 1
	v_mov_b32_e32 v148, 0
	v_mov_b32_e32 v149, 1
	global_atomic_add v148, v149, s[98:99]
	s_mov_b64 exec, -1

; #define PG8_STAGE(bufoff, gbase, voff) do { _Pragma("unroll") for (int _i = 0; _i < 2; ++_i) \
;         __builtin_amdgcn_global_load_lds((const unsigned*)((const char*)(gbase) + (voff)[_i]), (LAS unsigned*)(lds + (bufoff) + ldsw + _i * 8192), 16, 0, 0); } while (0)
; #define PG8_LDA(dst, b, h) do { _Pragma("unroll") for (int m = 0; m < 4; ++m) _Pragma("unroll") for (int k = 0; k < 2; ++k) dst[m][k] = *(const LAS bf16x8*)(lds + PG8_SA(b, h) + aoff + m * 2048 + k * 1024); } while (0)
; #define PG8_LDB(dst, b, h) do { _Pragma("unroll") for (int n = 0; n < 2; ++n) _Pragma("unroll") for (int k = 0; k < 2; ++k) dst[n][k] = *(const LAS bf16x8*)(lds + PG8_SB(b, h) + boff + n * 2048 + k * 1024); } while (0)
; #define PG8_MMA(ai, bj, At, Bt) do { __builtin_amdgcn_s_setprio(1); _Pragma("unroll") for (int m = 0; m < 4; ++m) _Pragma("unroll") for (int n = 0; n < 2; ++n) _Pragma("unroll") for (int k = 0; k < 2; ++k) \
;         acc[ai][bj][m][n] = __builtin_amdgcn_mfma_f32_16x16x32_bf16(Bt[n][k], At[m][k], acc[ai][bj][m][n], 0, 0, 0); __builtin_amdgcn_s_setprio(0); } while (0)
; #define PG8_WAIT_V(n) asm volatile("s_waitcnt vmcnt(" #n ")" ::: "memory")
; #define PG8_WAIT_L(n) asm volatile("s_waitcnt lgkmcnt(" #n ")" ::: "memory")
; template <class Epi, int LDA, int LDB, int KK>
; __device__ __forceinline__ void gemm_phase(int wv, LAS unsigned char* lds, const Gemm g, const StaticOrder& S, const Epi& E) {
;     ...
;           for (; t < tend; t += 2) {
;             const bool last = (t == nt - 2);
;             const char* a1 = cA + (size_t)(t + 1) * kstep;
;             const char* a2 = last ? nA : cA + (size_t)(t + 2) * kstep; const char* b2 = last ? nB : cB + (size_t)(t + 2) * kstep;
;             const char* a3 = a2 + kstep; const char* b3 = b2 + kstep;
;             PG8_LDB(B0, 0, 0); PG8_SCHED; PG8_LDA(At, 0, 0); PG8_STAGE(PG8_SA(1, 1), a1 + hstepA, voffA);
;             PG8_WAIT_L(8); PG8_BAR; PG8_WAIT_L(0); PG8_MMA(0, 0, At, B0); PG8_BAR; PG8_SCHED;
;             PG8_LDB(B1, 0, 1); PG8_STAGE(PG8_SB(0, 0), b2, voffB);
;             PG8_BAR; PG8_WAIT_L(0); PG8_MMA(0, 1, At, B1); PG8_BAR;
;             PG8_LDA(At, 0, 1); PG8_STAGE(PG8_SA(0, 0), a2, voffA);
;             PG8_BAR; PG8_WAIT_L(0); PG8_MMA(1, 0, At, B0); PG8_BAR; PG8_SCHED;
;             PG8_STAGE(PG8_SB(0, 1), b2 + hstepB, voffB);
;             PG8_WAIT_V(6); PG8_BAR; PG8_MMA(1, 1, At, B1); PG8_BAR;
.Ldown_loop:
	s_add_u32 s20, s18, 0x100
	s_addc_u32 s21, s19, 0
	s_cmpk_eq_i32 s56, 0x54
	s_cselect_b32 s25, s9, s21
	s_cselect_b32 s24, s8, s20
	s_cselect_b32 s23, s11, s55
	s_cselect_b32 s22, s10, s47
	s_waitcnt lgkmcnt(0)
	v_mfma_f32_16x16x32_bf16 v[128:131], v[132:135], v[148:151], v[128:131]
	ds_read_b128 v[202:205], v180 offset:1024
	v_mfma_f32_16x16x32_bf16 v[124:127], v[136:139], v[148:151], v[124:127]
	ds_read_b128 v[206:209], v180 offset:3072
	v_mfma_f32_16x16x32_bf16 v[120:123], v[140:143], v[148:151], v[120:123]
	ds_read_b128 v[210:213], v180 offset:17408
	v_mfma_f32_16x16x32_bf16 v[116:119], v[144:147], v[148:151], v[116:119]
	ds_read_b128 v[214:217], v180 offset:19456
	v_mfma_f32_16x16x32_bf16 v[112:115], v[132:135], v[152:155], v[112:115]
	ds_read_b128 v[164:167], v234 offset:1024
	v_mfma_f32_16x16x32_bf16 v[108:111], v[136:139], v[152:155], v[108:111]
	ds_read_b128 v[168:171], v234 offset:3072
	v_mfma_f32_16x16x32_bf16 v[104:107], v[140:143], v[152:155], v[104:107]
	ds_read_b128 v[172:175], v234 offset:5120
	v_mfma_f32_16x16x32_bf16 v[100:103], v[144:147], v[152:155], v[100:103]
	ds_read_b128 v[176:179], v234 offset:7168
	v_mfma_f32_16x16x32_bf16 v[96:99], v[132:135], v[156:159], v[96:99]
	v_mfma_f32_16x16x32_bf16 v[92:95], v[136:139], v[156:159], v[92:95]
	v_mfma_f32_16x16x32_bf16 v[88:91], v[140:143], v[156:159], v[88:91]
	v_mfma_f32_16x16x32_bf16 v[84:87], v[144:147], v[156:159], v[84:87]
	v_mfma_f32_16x16x32_bf16 v[80:83], v[132:135], v[160:163], v[80:83]
	v_mfma_f32_16x16x32_bf16 v[76:79], v[136:139], v[160:163], v[76:79]
	v_mfma_f32_16x16x32_bf16 v[72:75], v[140:143], v[160:163], v[72:75]
	v_mfma_f32_16x16x32_bf16 v[68:71], v[144:147], v[160:163], v[68:71]
	s_waitcnt vmcnt(8) lgkmcnt(0)
	s_barrier
	v_mfma_f32_16x16x32_bf16 v[128:131], v[202:205], v[164:167], v[128:131]
	ds_read_b128 v[148:151], v234 offset:16384
	v_mfma_f32_16x16x32_bf16 v[124:127], v[206:209], v[164:167], v[124:127]
	ds_read_b128 v[152:155], v234 offset:18432
	v_mfma_f32_16x16x32_bf16 v[120:123], v[210:213], v[164:167], v[120:123]
	ds_read_b128 v[156:159], v234 offset:20480
	v_mfma_f32_16x16x32_bf16 v[116:119], v[214:217], v[164:167], v[116:119]
	ds_read_b128 v[160:163], v234 offset:22528
	v_mfma_f32_16x16x32_bf16 v[112:115], v[202:205], v[168:171], v[112:115]
	s_add_i32 m0, s35, 0x10000
	v_mfma_f32_16x16x32_bf16 v[108:111], v[206:209], v[168:171], v[108:111]
	global_load_lds_dwordx4 v2, s[22:23]
	v_mfma_f32_16x16x32_bf16 v[104:107], v[210:213], v[168:171], v[104:107]
	v_mfma_f32_16x16x32_bf16 v[100:103], v[214:217], v[168:171], v[100:103]
	s_add_i32 m0, s35, 0x12000
	v_mfma_f32_16x16x32_bf16 v[96:99], v[202:205], v[172:175], v[96:99]
	global_load_lds_dwordx4 v190, s[22:23]
	v_mfma_f32_16x16x32_bf16 v[92:95], v[206:209], v[172:175], v[92:95]
	v_mfma_f32_16x16x32_bf16 v[88:91], v[210:213], v[172:175], v[88:91]
	s_mov_b32 m0, s35
	v_mfma_f32_16x16x32_bf16 v[84:87], v[214:217], v[172:175], v[84:87]
	global_load_lds_dwordx4 v0, s[24:25]
	v_mfma_f32_16x16x32_bf16 v[80:83], v[202:205], v[176:179], v[80:83]
	v_mfma_f32_16x16x32_bf16 v[76:79], v[206:209], v[176:179], v[76:79]
	v_mfma_f32_16x16x32_bf16 v[72:75], v[210:213], v[176:179], v[72:75]
	v_mfma_f32_16x16x32_bf16 v[68:71], v[214:217], v[176:179], v[68:71]
	s_waitcnt lgkmcnt(0)
	v_mfma_f32_16x16x32_bf16 v[64:67], v[132:135], v[148:151], v[64:67]
	ds_read_b128 v[164:167], v234 offset:17408
	v_mfma_f32_16x16x32_bf16 v[60:63], v[136:139], v[148:151], v[60:63]
	ds_read_b128 v[168:171], v234 offset:19456
	v_mfma_f32_16x16x32_bf16 v[56:59], v[140:143], v[148:151], v[56:59]
	ds_read_b128 v[172:175], v234 offset:21504
	v_mfma_f32_16x16x32_bf16 v[52:55], v[144:147], v[148:151], v[52:55]
	ds_read_b128 v[176:179], v234 offset:23552
	v_mfma_f32_16x16x32_bf16 v[48:51], v[132:135], v[152:155], v[48:51]
	s_add_i32 m0, s35, 0x2000
	v_mfma_f32_16x16x32_bf16 v[44:47], v[136:139], v[152:155], v[44:47]
	global_load_lds_dwordx4 v188, s[24:25]
	v_mfma_f32_16x16x32_bf16 v[40:43], v[140:143], v[152:155], v[40:43]
	v_mfma_f32_16x16x32_bf16 v[36:39], v[144:147], v[152:155], v[36:39]
	s_add_u32 s98, s22, 0x160000
	s_addc_u32 s99, s23, 0
	s_add_i32 m0, s35, 0x14000
	v_mfma_f32_16x16x32_bf16 v[32:35], v[132:135], v[156:159], v[32:35]
	global_load_lds_dwordx4 v2, s[98:99]
	v_mfma_f32_16x16x32_bf16 v[28:31], v[136:139], v[156:159], v[28:31]
	v_mfma_f32_16x16x32_bf16 v[24:27], v[140:143], v[156:159], v[24:27]
	s_add_i32 m0, s35, 0x16000
	v_mfma_f32_16x16x32_bf16 v[20:23], v[144:147], v[156:159], v[20:23]
	global_load_lds_dwordx4 v190, s[98:99]
	v_mfma_f32_16x16x32_bf16 v[16:19], v[132:135], v[160:163], v[16:19]
	v_mfma_f32_16x16x32_bf16 v[12:15], v[136:139], v[160:163], v[12:15]
	v_mfma_f32_16x16x32_bf16 v[8:11], v[140:143], v[160:163], v[8:11]
	v_mfma_f32_16x16x32_bf16 v[4:7], v[144:147], v[160:163], v[4:7]
	s_waitcnt vmcnt(8) lgkmcnt(0)
	s_barrier
; #define PG8_STAGE(bufoff, gbase, voff) do { _Pragma("unroll") for (int _i = 0; _i < 2; ++_i) \
;         __builtin_amdgcn_global_load_lds((const unsigned*)((const char*)(gbase) + (voff)[_i]), (LAS unsigned*)(lds + (bufoff) + ldsw + _i * 8192), 16, 0, 0); } while (0)
; #define PG8_LDA(dst, b, h) do { _Pragma("unroll") for (int m = 0; m < 4; ++m) _Pragma("unroll") for (int k = 0; k < 2; ++k) dst[m][k] = *(const LAS bf16x8*)(lds + PG8_SA(b, h) + aoff + m * 2048 + k * 1024); } while (0)
; #define PG8_LDB(dst, b, h) do { _Pragma("unroll") for (int n = 0; n < 2; ++n) _Pragma("unroll") for (int k = 0; k < 2; ++k) dst[n][k] = *(const LAS bf16x8*)(lds + PG8_SB(b, h) + boff + n * 2048 + k * 1024); } while (0)
; #define PG8_MMA(ai, bj, At, Bt) do { __builtin_amdgcn_s_setprio(1); _Pragma("unroll") for (int m = 0; m < 4; ++m) _Pragma("unroll") for (int n = 0; n < 2; ++n) _Pragma("unroll") for (int k = 0; k < 2; ++k) \
;         acc[ai][bj][m][n] = __builtin_amdgcn_mfma_f32_16x16x32_bf16(Bt[n][k], At[m][k], acc[ai][bj][m][n], 0, 0, 0); __builtin_amdgcn_s_setprio(0); } while (0)
; #define PG8_WAIT_V(n) asm volatile("s_waitcnt vmcnt(" #n ")" ::: "memory")
; #define PG8_WAIT_L(n) asm volatile("s_waitcnt lgkmcnt(" #n ")" ::: "memory")
; #define PG8_BAR __builtin_amdgcn_s_barrier()
; #define PG8_SCHED __builtin_amdgcn_sched_barrier(0)
; template <class Epi, int LDA, int LDB, int KK>
; __device__ __forceinline__ void gemm_phase(int wv, LAS unsigned char* lds, const Gemm g, const StaticOrder& S, const Epi& E) {
;     ...
;             PG8_LDB(B0, 1, 0); PG8_SCHED; PG8_LDA(At, 1, 0); PG8_STAGE(PG8_SA(0, 1), a2 + hstepA, voffA);
;             PG8_WAIT_L(8); PG8_BAR; PG8_WAIT_L(0); PG8_MMA(0, 0, At, B0); PG8_BAR; PG8_SCHED;
;             PG8_LDB(B1, 1, 1); PG8_STAGE(PG8_SB(1, 0), b3, voffB);
;             PG8_BAR; PG8_WAIT_L(0); PG8_MMA(0, 1, At, B1); PG8_BAR;
;             PG8_LDA(At, 1, 1); PG8_STAGE(PG8_SA(1, 0), a3, voffA);
;             PG8_BAR; PG8_WAIT_L(0); PG8_MMA(1, 0, At, B0); PG8_BAR; PG8_SCHED;
;             PG8_STAGE(PG8_SB(1, 1), b3 + hstepB, voffB);
;             PG8_WAIT_V(6); PG8_BAR; PG8_MMA(1, 1, At, B1); PG8_BAR;
	v_mfma_f32_16x16x32_bf16 v[64:67], v[202:205], v[164:167], v[64:67]
	ds_read_b128 v[132:135], v180 offset:32768
	v_mfma_f32_16x16x32_bf16 v[60:63], v[206:209], v[164:167], v[60:63]
	ds_read_b128 v[136:139], v180 offset:34816
	v_mfma_f32_16x16x32_bf16 v[56:59], v[210:213], v[164:167], v[56:59]
	ds_read_b128 v[140:143], v180 offset:49152
	v_mfma_f32_16x16x32_bf16 v[52:55], v[214:217], v[164:167], v[52:55]
	ds_read_b128 v[144:147], v180 offset:51200
	v_mfma_f32_16x16x32_bf16 v[48:51], v[202:205], v[168:171], v[48:51]
	ds_read_b128 v[148:151], v234 offset:32768
	v_mfma_f32_16x16x32_bf16 v[44:47], v[206:209], v[168:171], v[44:47]
	ds_read_b128 v[152:155], v234 offset:34816
	v_mfma_f32_16x16x32_bf16 v[40:43], v[210:213], v[168:171], v[40:43]
	ds_read_b128 v[156:159], v234 offset:36864
	v_mfma_f32_16x16x32_bf16 v[36:39], v[214:217], v[168:171], v[36:39]
	ds_read_b128 v[160:163], v234 offset:38912
	v_mfma_f32_16x16x32_bf16 v[32:35], v[202:205], v[172:175], v[32:35]
	s_add_u32 s98, s24, 0x2c0000
	s_addc_u32 s99, s25, 0
	s_add_i32 m0, s35, 0x4000
	v_mfma_f32_16x16x32_bf16 v[28:31], v[206:209], v[172:175], v[28:31]
	global_load_lds_dwordx4 v0, s[98:99]
	v_mfma_f32_16x16x32_bf16 v[24:27], v[210:213], v[172:175], v[24:27]
	v_mfma_f32_16x16x32_bf16 v[20:23], v[214:217], v[172:175], v[20:23]
	s_add_i32 m0, s35, 0x6000
	v_mfma_f32_16x16x32_bf16 v[16:19], v[202:205], v[176:179], v[16:19]
	global_load_lds_dwordx4 v188, s[98:99]
	v_mfma_f32_16x16x32_bf16 v[12:15], v[206:209], v[176:179], v[12:15]
	v_mfma_f32_16x16x32_bf16 v[8:11], v[210:213], v[176:179], v[8:11]
	v_mfma_f32_16x16x32_bf16 v[4:7], v[214:217], v[176:179], v[4:7]
	s_waitcnt lgkmcnt(0)
	v_mfma_f32_16x16x32_bf16 v[128:131], v[132:135], v[148:151], v[128:131]
	ds_read_b128 v[202:205], v180 offset:33792
	v_mfma_f32_16x16x32_bf16 v[124:127], v[136:139], v[148:151], v[124:127]
	ds_read_b128 v[206:209], v180 offset:35840
	v_mfma_f32_16x16x32_bf16 v[120:123], v[140:143], v[148:151], v[120:123]
	ds_read_b128 v[210:213], v180 offset:50176
	v_mfma_f32_16x16x32_bf16 v[116:119], v[144:147], v[148:151], v[116:119]
	ds_read_b128 v[214:217], v180 offset:52224
	v_mfma_f32_16x16x32_bf16 v[112:115], v[132:135], v[152:155], v[112:115]
	ds_read_b128 v[164:167], v234 offset:33792
	v_mfma_f32_16x16x32_bf16 v[108:111], v[136:139], v[152:155], v[108:111]
	ds_read_b128 v[168:171], v234 offset:35840
	v_mfma_f32_16x16x32_bf16 v[104:107], v[140:143], v[152:155], v[104:107]
	ds_read_b128 v[172:175], v234 offset:37888
	v_mfma_f32_16x16x32_bf16 v[100:103], v[144:147], v[152:155], v[100:103]
	ds_read_b128 v[176:179], v234 offset:39936
	v_mfma_f32_16x16x32_bf16 v[96:99], v[132:135], v[156:159], v[96:99]
	v_mfma_f32_16x16x32_bf16 v[92:95], v[136:139], v[156:159], v[92:95]
	v_mfma_f32_16x16x32_bf16 v[88:91], v[140:143], v[156:159], v[88:91]
	v_mfma_f32_16x16x32_bf16 v[84:87], v[144:147], v[156:159], v[84:87]
	v_mfma_f32_16x16x32_bf16 v[80:83], v[132:135], v[160:163], v[80:83]
	v_mfma_f32_16x16x32_bf16 v[76:79], v[136:139], v[160:163], v[76:79]
	v_mfma_f32_16x16x32_bf16 v[72:75], v[140:143], v[160:163], v[72:75]
	v_mfma_f32_16x16x32_bf16 v[68:71], v[144:147], v[160:163], v[68:71]
	s_waitcnt vmcnt(8) lgkmcnt(0)
	s_barrier
	v_mfma_f32_16x16x32_bf16 v[128:131], v[202:205], v[164:167], v[128:131]
	ds_read_b128 v[148:151], v234 offset:49152
	v_mfma_f32_16x16x32_bf16 v[124:127], v[206:209], v[164:167], v[124:127]
	ds_read_b128 v[152:155], v234 offset:51200
	v_mfma_f32_16x16x32_bf16 v[120:123], v[210:213], v[164:167], v[120:123]
	ds_read_b128 v[156:159], v234 offset:53248
	v_mfma_f32_16x16x32_bf16 v[116:119], v[214:217], v[164:167], v[116:119]
	ds_read_b128 v[160:163], v234 offset:55296
	v_mfma_f32_16x16x32_bf16 v[112:115], v[202:205], v[168:171], v[112:115]
	s_add_i32 m0, s35, 0x17f80
	v_mfma_f32_16x16x32_bf16 v[108:111], v[206:209], v[168:171], v[108:111]
	global_load_lds_dwordx4 v2, s[22:23] offset:128
	v_mfma_f32_16x16x32_bf16 v[104:107], v[210:213], v[168:171], v[104:107]
	v_mfma_f32_16x16x32_bf16 v[100:103], v[214:217], v[168:171], v[100:103]
	s_add_i32 m0, s35, 0x19f80
	v_mfma_f32_16x16x32_bf16 v[96:99], v[202:205], v[172:175], v[96:99]
	global_load_lds_dwordx4 v190, s[22:23] offset:128
	v_mfma_f32_16x16x32_bf16 v[92:95], v[206:209], v[172:175], v[92:95]
	v_mfma_f32_16x16x32_bf16 v[88:91], v[210:213], v[172:175], v[88:91]
	s_add_i32 m0, s35, 0x7f80
	v_mfma_f32_16x16x32_bf16 v[84:87], v[214:217], v[172:175], v[84:87]
	global_load_lds_dwordx4 v0, s[24:25] offset:128
	v_mfma_f32_16x16x32_bf16 v[80:83], v[202:205], v[176:179], v[80:83]
	v_mfma_f32_16x16x32_bf16 v[76:79], v[206:209], v[176:179], v[76:79]
	v_mfma_f32_16x16x32_bf16 v[72:75], v[210:213], v[176:179], v[72:75]
	v_mfma_f32_16x16x32_bf16 v[68:71], v[214:217], v[176:179], v[68:71]
	s_waitcnt lgkmcnt(0)
	v_mfma_f32_16x16x32_bf16 v[64:67], v[132:135], v[148:151], v[64:67]
	ds_read_b128 v[164:167], v234 offset:50176
	v_mfma_f32_16x16x32_bf16 v[60:63], v[136:139], v[148:151], v[60:63]
	ds_read_b128 v[168:171], v234 offset:52224
	v_mfma_f32_16x16x32_bf16 v[56:59], v[140:143], v[148:151], v[56:59]
	ds_read_b128 v[172:175], v234 offset:54272
	v_mfma_f32_16x16x32_bf16 v[52:55], v[144:147], v[148:151], v[52:55]
	ds_read_b128 v[176:179], v234 offset:56320
	v_mfma_f32_16x16x32_bf16 v[48:51], v[132:135], v[152:155], v[48:51]
	s_add_i32 m0, s35, 0x9f80
	v_mfma_f32_16x16x32_bf16 v[44:47], v[136:139], v[152:155], v[44:47]
	global_load_lds_dwordx4 v188, s[24:25] offset:128
	v_mfma_f32_16x16x32_bf16 v[40:43], v[140:143], v[152:155], v[40:43]
	v_mfma_f32_16x16x32_bf16 v[36:39], v[144:147], v[152:155], v[36:39]
	s_add_u32 s98, s22, 0x160000
	s_addc_u32 s99, s23, 0
	s_add_i32 m0, s35, 0x1bf80
	v_mfma_f32_16x16x32_bf16 v[32:35], v[132:135], v[156:159], v[32:35]
	global_load_lds_dwordx4 v2, s[98:99] offset:128
	v_mfma_f32_16x16x32_bf16 v[28:31], v[136:139], v[156:159], v[28:31]
	v_mfma_f32_16x16x32_bf16 v[24:27], v[140:143], v[156:159], v[24:27]
	s_add_i32 m0, s35, 0x1df80
	v_mfma_f32_16x16x32_bf16 v[20:23], v[144:147], v[156:159], v[20:23]
	global_load_lds_dwordx4 v190, s[98:99] offset:128
	v_mfma_f32_16x16x32_bf16 v[16:19], v[132:135], v[160:163], v[16:19]
	v_mfma_f32_16x16x32_bf16 v[12:15], v[136:139], v[160:163], v[12:15]
	v_mfma_f32_16x16x32_bf16 v[8:11], v[140:143], v[160:163], v[8:11]
	v_mfma_f32_16x16x32_bf16 v[4:7], v[144:147], v[160:163], v[4:7]
	s_waitcnt vmcnt(8) lgkmcnt(0)
	s_barrier
; #define LAS __attribute__((address_space(3)))
; #define PG8_STAGE(bufoff, gbase, voff) do { _Pragma("unroll") for (int _i = 0; _i < 2; ++_i) \
;         __builtin_amdgcn_global_load_lds((const unsigned*)((const char*)(gbase) + (voff)[_i]), (LAS unsigned*)(lds + (bufoff) + ldsw + _i * 8192), 16, 0, 0); } while (0)
; #define PG8_LDA(dst, b, h) do { _Pragma("unroll") for (int m = 0; m < 4; ++m) _Pragma("unroll") for (int k = 0; k < 2; ++k) dst[m][k] = *(const LAS bf16x8*)(lds + PG8_SA(b, h) + aoff + m * 2048 + k * 1024); } while (0)
; #define PG8_MMA(ai, bj, At, Bt) do { __builtin_amdgcn_s_setprio(1); _Pragma("unroll") for (int m = 0; m < 4; ++m) _Pragma("unroll") for (int n = 0; n < 2; ++n) _Pragma("unroll") for (int k = 0; k < 2; ++k) \
;         acc[ai][bj][m][n] = __builtin_amdgcn_mfma_f32_16x16x32_bf16(Bt[n][k], At[m][k], acc[ai][bj][m][n], 0, 0, 0); __builtin_amdgcn_s_setprio(0); } while (0)
; #define PG8_WAIT_V(n) asm volatile("s_waitcnt vmcnt(" #n ")" ::: "memory")
; #define PG8_WAIT_L(n) asm volatile("s_waitcnt lgkmcnt(" #n ")" ::: "memory")
; #define PG8_BAR __builtin_amdgcn_s_barrier()
; #define PG8_SCHED __builtin_amdgcn_sched_barrier(0)
; template <class Epi, int LDA, int LDB, int KK>
; __device__ __forceinline__ void gemm_phase(int wv, LAS unsigned char* lds, const Gemm g, const StaticOrder& S, const Epi& E) {
;     ...
;             PG8_LDA(At, 1, 1); PG8_STAGE(PG8_SA(1, 0), a3, voffA);
;             PG8_BAR; PG8_WAIT_L(0); PG8_MMA(1, 0, At, B0); PG8_BAR; PG8_SCHED;
;             PG8_STAGE(PG8_SB(1, 1), b3 + hstepB, voffB);
;             PG8_WAIT_V(6); PG8_BAR; PG8_MMA(1, 1, At, B1); PG8_BAR;
;           }
;           if constexpr (Epi::HAS_MID) { if (seg < Epi::NSEG - 1) E.mid(acc, cur, seg, wr, wc, fr, fq); }
;         }
;         E(acc, cur, wr, wc, fr, fq, (const LAS float*)(lds + 131072 + (ui % 3) * 1024));
	v_mfma_f32_16x16x32_bf16 v[64:67], v[202:205], v[164:167], v[64:67]
	ds_read_b128 v[132:135], v180 offset:0
	v_mfma_f32_16x16x32_bf16 v[60:63], v[206:209], v[164:167], v[60:63]
	ds_read_b128 v[136:139], v180 offset:2048
	v_mfma_f32_16x16x32_bf16 v[56:59], v[210:213], v[164:167], v[56:59]
	ds_read_b128 v[140:143], v180 offset:16384
	v_mfma_f32_16x16x32_bf16 v[52:55], v[214:217], v[164:167], v[52:55]
	ds_read_b128 v[144:147], v180 offset:18432
	v_mfma_f32_16x16x32_bf16 v[48:51], v[202:205], v[168:171], v[48:51]
	ds_read_b128 v[148:151], v234 offset:0
	v_mfma_f32_16x16x32_bf16 v[44:47], v[206:209], v[168:171], v[44:47]
	ds_read_b128 v[152:155], v234 offset:2048
	v_mfma_f32_16x16x32_bf16 v[40:43], v[210:213], v[168:171], v[40:43]
	ds_read_b128 v[156:159], v234 offset:4096
	v_mfma_f32_16x16x32_bf16 v[36:39], v[214:217], v[168:171], v[36:39]
	ds_read_b128 v[160:163], v234 offset:6144
	v_mfma_f32_16x16x32_bf16 v[32:35], v[202:205], v[172:175], v[32:35]
	s_add_u32 s98, s24, 0x2c0000
	s_addc_u32 s99, s25, 0
	s_add_i32 m0, s35, 0xbf80
	v_mfma_f32_16x16x32_bf16 v[28:31], v[206:209], v[172:175], v[28:31]
	global_load_lds_dwordx4 v0, s[98:99] offset:128
	v_mfma_f32_16x16x32_bf16 v[24:27], v[210:213], v[172:175], v[24:27]
	v_mfma_f32_16x16x32_bf16 v[20:23], v[214:217], v[172:175], v[20:23]
	s_add_i32 m0, s35, 0xdf80
	v_mfma_f32_16x16x32_bf16 v[16:19], v[202:205], v[176:179], v[16:19]
	global_load_lds_dwordx4 v188, s[98:99] offset:128
	v_mfma_f32_16x16x32_bf16 v[12:15], v[206:209], v[176:179], v[12:15]
	v_mfma_f32_16x16x32_bf16 v[8:11], v[210:213], v[176:179], v[8:11]
	v_mfma_f32_16x16x32_bf16 v[4:7], v[214:217], v[176:179], v[4:7]
	s_add_i32 s56, s56, 2
	s_add_u32 s47, s47, 0x100
	s_addc_u32 s55, s55, 0
	s_cmpk_gt_u32 s56, 0x55
	s_mov_b64 s[18:19], s[20:21]
	s_cbranch_scc0 .Ldown_loop
	s_waitcnt lgkmcnt(0)
	s_cmp_eq_u32 s100, 0
	s_cbranch_scc1 .Ldn_epi
	s_cmp_eq_u32 s100, 4
	s_cbranch_scc1 .Ldn_owner
	s_and_b32 s98, s81, 15
	s_mul_i32 s98, s98, 3
	s_add_u32 s98, s98, s100
	s_sub_u32 s98, s98, 1
	s_lshl_b32 s98, s98, 18
	s_add_u32 s98, s98, 0x1f000000
	s_add_u32 s98, s14, s98
	s_addc_u32 s99, s15, 0
	v_mbcnt_lo_u32_b32 v132, -1, 0
	v_mbcnt_hi_u32_b32 v132, -1, v132
	v_lshl_or_b32 v132, s95, 6, v132
	v_lshlrev_b32_e32 v132, 4, v132
	global_store_dwordx4 v132, v[4:7], s[98:99] sc0 sc1
	v_add_u32_e32 v132, 0x2000, v132
	global_store_dwordx4 v132, v[8:11], s[98:99] sc0 sc1
	v_add_u32_e32 v132, 0x2000, v132
	global_store_dwordx4 v132, v[12:15], s[98:99] sc0 sc1
	v_add_u32_e32 v132, 0x2000, v132
	global_store_dwordx4 v132, v[16:19], s[98:99] sc0 sc1
	v_add_u32_e32 v132, 0x2000, v132
	global_store_dwordx4 v132, v[20:23], s[98:99] sc0 sc1
	v_add_u32_e32 v132, 0x2000, v132
	global_store_dwordx4 v132, v[24:27], s[98:99] sc0 sc1
	v_add_u32_e32 v132, 0x2000, v132
	global_store_dwordx4 v132, v[28:31], s[98:99] sc0 sc1
	v_add_u32_e32 v132, 0x2000, v132
	global_store_dwordx4 v132, v[32:35], s[98:99] sc0 sc1
	v_add_u32_e32 v132, 0x2000, v132
	global_store_dwordx4 v132, v[36:39], s[98:99] sc0 sc1
	v_add_u32_e32 v132, 0x2000, v132
	global_store_dwordx4 v132, v[40:43], s[98:99] sc0 sc1
	v_add_u32_e32 v132, 0x2000, v132
	global_store_dwordx4 v132, v[44:47], s[98:99] sc0 sc1
	v_add_u32_e32 v132, 0x2000, v132
	global_store_dwordx4 v132, v[48:51], s[98:99] sc0 sc1
	v_add_u32_e32 v132, 0x2000, v132
	global_store_dwordx4 v132, v[52:55], s[98:99] sc0 sc1
	v_add_u32_e32 v132, 0x2000, v132
	global_store_dwordx4 v132, v[56:59], s[98:99] sc0 sc1
	v_add_u32_e32 v132, 0x2000, v132
	global_store_dwordx4 v132, v[60:63], s[98:99] sc0 sc1
	v_add_u32_e32 v132, 0x2000, v132
	global_store_dwordx4 v132, v[64:67], s[98:99] sc0 sc1
	v_add_u32_e32 v132, 0x2000, v132
	global_store_dwordx4 v132, v[68:71], s[98:99] sc0 sc1
	v_add_u32_e32 v132, 0x2000, v132
	global_store_dwordx4 v132, v[72:75], s[98:99] sc0 sc1
	v_add_u32_e32 v132, 0x2000, v132
	global_store_dwordx4 v132, v[76:79], s[98:99] sc0 sc1
	v_add_u32_e32 v132, 0x2000, v132
	global_store_dwordx4 v132, v[80:83], s[98:99] sc0 sc1
	v_add_u32_e32 v132, 0x2000, v132
	global_store_dwordx4 v132, v[84:87], s[98:99] sc0 sc1
	v_add_u32_e32 v132, 0x2000, v132
	global_store_dwordx4 v132, v[88:91], s[98:99] sc0 sc1
	v_add_u32_e32 v132, 0x2000, v132
	global_store_dwordx4 v132, v[92:95], s[98:99] sc0 sc1
	v_add_u32_e32 v132, 0x2000, v132
	global_store_dwordx4 v132, v[96:99], s[98:99] sc0 sc1
	v_add_u32_e32 v132, 0x2000, v132
	global_store_dwordx4 v132, v[100:103], s[98:99] sc0 sc1
	v_add_u32_e32 v132, 0x2000, v132
	global_store_dwordx4 v132, v[104:107], s[98:99] sc0 sc1
	v_add_u32_e32 v132, 0x2000, v132
	global_store_dwordx4 v132, v[108:111], s[98:99] sc0 sc1
	v_add_u32_e32 v132, 0x2000, v132
	global_store_dwordx4 v132, v[112:115], s[98:99] sc0 sc1
	v_add_u32_e32 v132, 0x2000, v132
	global_store_dwordx4 v132, v[116:119], s[98:99] sc0 sc1
	v_add_u32_e32 v132, 0x2000, v132
	global_store_dwordx4 v132, v[120:123], s[98:99] sc0 sc1
	v_add_u32_e32 v132, 0x2000, v132
	global_store_dwordx4 v132, v[124:127], s[98:99] sc0 sc1
	v_add_u32_e32 v132, 0x2000, v132
	global_store_dwordx4 v132, v[128:131], s[98:99] sc0 sc1
	s_waitcnt vmcnt(0)
	s_barrier
	s_cmp_lg_u32 s95, 0
	s_cbranch_scc1 .Ldn_p_done
	s_and_b32 s98, s81, 15
	s_lshl_b32 s98, s98, 2
	s_add_u32 s98, s98, 0x285da900
	s_add_u32 s98, s14, s98
	s_addc_u32 s99, s15, 0
	s_mov_b64 exec, 1
	v_mov_b32_e32 v132, 0
	v_mov_b32_e32 v133, 1
	global_atomic_add v132, v133, s[98:99]
	s_mov_b64 exec, -1
